# merge GEMM epilogue (EpiWo) rewritten by hand: straight-line gate ratios, all gate loads in one round trip; plus in_proj epilogue trims and first-K-trip C=0 instead of accumulator zeroing
# speedup vs baseline: 1.0280x; 1.0280x over previous
.LBB0_313:
	s_ashr_i32 s57, s56, 31
	s_lshl_b64 s[34:35], s[56:57], 19
	s_add_u32 s70, s26, s34
	s_addc_u32 s71, s27, s35
	s_and_b64 s[34:35], exec, s[12:13]
	s_cselect_b32 s57, s11, s71
	s_cselect_b32 s66, s10, s70
	s_ashr_i32 s63, s62, 31
	s_lshl_b64 s[34:35], s[62:63], 19
	s_add_u32 s72, s28, s34
	s_addc_u32 s73, s29, s35
	s_and_b64 s[34:35], exec, s[12:13]
	s_cselect_b32 s63, s9, s73
	s_cselect_b32 s90, s8, s72
	s_lshl_b32 s34, s56, 4
	s_ashr_i32 s35, s34, 31
	s_cmp_lt_i32 s56, 64
	s_cselect_b32 s91, 32, 0x100
	s_or_b64 s[12:13], s[12:13], s[46:47]
	s_lshl_b64 s[34:35], s[34:35], 2
	s_add_u32 s74, s61, s34
	s_addc_u32 s75, s55, s35
	s_mov_b32 s89, 0
	s_waitcnt vmcnt(0)
.Lpeel_a:
	s_mov_b64 s[34:35], -1
	s_or_b32 s92, s89, 1
	s_lshl_b64 s[76:77], s[92:93], 7
	s_add_u32 s0, s10, s76
	s_addc_u32 s54, s11, s77
	s_add_i32 s92, s89, 2
	s_lshl_b64 s[78:79], s[92:93], 7
	s_add_u32 s80, s10, s78
	s_addc_u32 s81, s11, s79
	s_and_b64 s[76:77], s[34:35], exec
	s_cselect_b32 s77, s81, s57
	s_cselect_b32 s76, s80, s66
	s_add_u32 s78, s8, s78
	s_addc_u32 s79, s9, s79
	s_and_b64 s[34:35], s[34:35], exec
	s_cselect_b32 s35, s79, s63
	s_cselect_b32 s34, s78, s90
	s_add_i32 s80, 0, 0x10000
	s_add_i32 s81, 0, 0x14000
	v_add_u32_e32 v12, s80, v205
	v_add_u32_e32 v28, s81, v205
	ds_read_b128 v[0:3], v12
	ds_read_b128 v[4:7], v12 offset:1024
	ds_read_b128 v[8:11], v12 offset:2048
	ds_read_b128 v[12:15], v12 offset:3072
	ds_read_b128 v[16:19], v28
	ds_read_b128 v[20:23], v28 offset:1024
	ds_read_b128 v[24:27], v28 offset:2048
	ds_read_b128 v[28:31], v28 offset:3072
	s_add_u32 s78, s0, 0x40000
	s_addc_u32 s79, s54, 0
	v_lshl_add_u64 v[202:203], s[78:79], 0, v[184:185]
	s_add_i32 m0, s96, 0xc000
	ds_read_b128 v[166:169], v209
	ds_read_b128 v[170:173], v209 offset:1024
	ds_read_b128 v[174:177], v209 offset:2048
	ds_read_b128 v[178:181], v209 offset:3072
	ds_read_b128 v[196:199], v209 offset:4096
	ds_read_b128 v[210:213], v209 offset:5120
	ds_read_b128 v[244:247], v209 offset:6144
	ds_read_b128 v[248:251], v209 offset:7168
	global_load_lds_dwordx4 v[202:203], off
	v_lshl_add_u64 v[202:203], s[78:79], 0, v[186:187]
	s_add_i32 m0, s96, 0xe000
	s_nop 0
	global_load_lds_dwordx4 v[202:203], off
	s_waitcnt vmcnt(8)
	s_waitcnt lgkmcnt(0)
	s_barrier
	s_setprio 1
	s_waitcnt lgkmcnt(0)
	v_mfma_f32_16x16x32_bf16 v[162:165], v[0:3], v[166:169], 0
	v_mfma_f32_16x16x32_bf16 v[158:161], v[8:11], v[166:169], 0
	v_mfma_f32_16x16x32_bf16 v[146:149], v[0:3], v[174:177], 0
	v_mfma_f32_16x16x32_bf16 v[142:145], v[8:11], v[174:177], 0
	v_mfma_f32_16x16x32_bf16 v[130:133], v[0:3], v[196:199], 0
	v_mfma_f32_16x16x32_bf16 v[126:129], v[8:11], v[196:199], 0
	v_mfma_f32_16x16x32_bf16 v[114:117], v[0:3], v[244:247], 0
	v_mfma_f32_16x16x32_bf16 v[110:113], v[8:11], v[244:247], 0
	v_mfma_f32_16x16x32_bf16 v[162:165], v[4:7], v[170:173], v[162:165]
	v_mfma_f32_16x16x32_bf16 v[158:161], v[12:15], v[170:173], v[158:161]
	v_mfma_f32_16x16x32_bf16 v[146:149], v[4:7], v[178:181], v[146:149]
	v_mfma_f32_16x16x32_bf16 v[142:145], v[12:15], v[178:181], v[142:145]
	v_mfma_f32_16x16x32_bf16 v[130:133], v[4:7], v[210:213], v[130:133]
	v_mfma_f32_16x16x32_bf16 v[126:129], v[12:15], v[210:213], v[126:129]
	v_mfma_f32_16x16x32_bf16 v[114:117], v[4:7], v[248:251], v[114:117]
	v_mfma_f32_16x16x32_bf16 v[110:113], v[12:15], v[248:251], v[110:113]
	s_setprio 0
	s_setprio 1
	v_mfma_f32_16x16x32_bf16 v[154:157], v[16:19], v[166:169], 0
	v_mfma_f32_16x16x32_bf16 v[150:153], v[24:27], v[166:169], 0
	v_mfma_f32_16x16x32_bf16 v[138:141], v[16:19], v[174:177], 0
	v_mfma_f32_16x16x32_bf16 v[134:137], v[24:27], v[174:177], 0
	v_mfma_f32_16x16x32_bf16 v[122:125], v[16:19], v[196:199], 0
	v_mfma_f32_16x16x32_bf16 v[118:121], v[24:27], v[196:199], 0
	v_mfma_f32_16x16x32_bf16 v[106:109], v[16:19], v[244:247], 0
	v_mfma_f32_16x16x32_bf16 v[102:105], v[24:27], v[244:247], 0
	v_mfma_f32_16x16x32_bf16 v[154:157], v[20:23], v[170:173], v[154:157]
	v_mfma_f32_16x16x32_bf16 v[150:153], v[28:31], v[170:173], v[150:153]
	v_mfma_f32_16x16x32_bf16 v[138:141], v[20:23], v[178:181], v[138:141]
	v_mfma_f32_16x16x32_bf16 v[134:137], v[28:31], v[178:181], v[134:137]
	v_mfma_f32_16x16x32_bf16 v[122:125], v[20:23], v[210:213], v[122:125]
	v_mfma_f32_16x16x32_bf16 v[118:121], v[28:31], v[210:213], v[118:121]
	v_mfma_f32_16x16x32_bf16 v[106:109], v[20:23], v[248:251], v[106:109]
	v_mfma_f32_16x16x32_bf16 v[102:105], v[28:31], v[248:251], v[102:105]
	s_setprio 0
	s_barrier
	s_add_i32 s0, s80, s95
	v_lshl_add_u64 v[202:203], s[34:35], 0, v[182:183]
	s_mov_b32 m0, s0
	ds_read_b128 v[166:169], v209 offset:16384
	ds_read_b128 v[170:173], v209 offset:17408
	ds_read_b128 v[174:177], v209 offset:18432
	ds_read_b128 v[178:181], v209 offset:19456
	ds_read_b128 v[196:199], v209 offset:20480
	ds_read_b128 v[210:213], v209 offset:21504
	ds_read_b128 v[244:247], v209 offset:22528
	ds_read_b128 v[248:251], v209 offset:23552
	global_load_lds_dwordx4 v[202:203], off
	s_add_i32 m0, s0, 0x2000
	s_add_u32 s78, s34, 0x40000
	v_lshl_add_u64 v[214:215], s[34:35], 0, v[34:35]
	s_addc_u32 s79, s35, 0
	s_add_i32 s0, s81, s95
	global_load_lds_dwordx4 v[214:215], off
	v_lshl_add_u64 v[218:219], s[78:79], 0, v[182:183]
	s_mov_b32 m0, s0
	v_lshl_add_u64 v[222:223], s[76:77], 0, v[184:185]
	global_load_lds_dwordx4 v[218:219], off
	v_lshl_add_u64 v[218:219], s[78:79], 0, v[34:35]
	s_add_i32 m0, s0, 0x2000
	v_lshl_add_u64 v[236:237], s[76:77], 0, v[186:187]
	global_load_lds_dwordx4 v[218:219], off
	s_mov_b32 m0, s96
	s_nop 0
	global_load_lds_dwordx4 v[222:223], off
	s_mov_b32 m0, s97
	s_nop 0
	global_load_lds_dwordx4 v[236:237], off
	s_waitcnt vmcnt(8)
	s_waitcnt lgkmcnt(0)
	s_barrier
	s_setprio 1
	s_waitcnt lgkmcnt(0)
	v_mfma_f32_16x16x32_bf16 v[98:101], v[0:3], v[166:169], 0
	v_mfma_f32_16x16x32_bf16 v[94:97], v[8:11], v[166:169], 0
	v_mfma_f32_16x16x32_bf16 v[82:85], v[0:3], v[174:177], 0
	v_mfma_f32_16x16x32_bf16 v[78:81], v[8:11], v[174:177], 0
	v_mfma_f32_16x16x32_bf16 v[66:69], v[0:3], v[196:199], 0
	v_mfma_f32_16x16x32_bf16 v[62:65], v[8:11], v[196:199], 0
	v_mfma_f32_16x16x32_bf16 v[0:3], v[0:3], v[244:247], 0
	v_mfma_f32_16x16x32_bf16 v[98:101], v[4:7], v[170:173], v[98:101]
	v_mfma_f32_16x16x32_bf16 v[94:97], v[12:15], v[170:173], v[94:97]
	v_mfma_f32_16x16x32_bf16 v[82:85], v[4:7], v[178:181], v[82:85]
	v_mfma_f32_16x16x32_bf16 v[78:81], v[12:15], v[178:181], v[78:81]
	v_mfma_f32_16x16x32_bf16 v[66:69], v[4:7], v[210:213], v[66:69]
	v_mfma_f32_16x16x32_bf16 v[62:65], v[12:15], v[210:213], v[62:65]
	v_mfma_f32_16x16x32_bf16 v[0:3], v[4:7], v[248:251], v[0:3]
	v_mfma_f32_16x16x32_bf16 v[4:7], v[8:11], v[244:247], 0
	v_mfma_f32_16x16x32_bf16 v[4:7], v[12:15], v[248:251], v[4:7]
	s_setprio 0
	s_setprio 1
	v_mfma_f32_16x16x32_bf16 v[46:49], v[16:19], v[174:177], 0
	v_mfma_f32_16x16x32_bf16 v[74:77], v[20:23], v[178:181], v[46:49]
	v_mfma_f32_16x16x32_bf16 v[46:49], v[24:27], v[174:177], 0
	v_mfma_f32_16x16x32_bf16 v[70:73], v[28:31], v[178:181], v[46:49]
	v_mfma_f32_16x16x32_bf16 v[46:49], v[16:19], v[196:199], 0
	v_mfma_f32_16x16x32_bf16 v[8:11], v[16:19], v[166:169], 0
	v_mfma_f32_16x16x32_bf16 v[58:61], v[20:23], v[210:213], v[46:49]
	v_mfma_f32_16x16x32_bf16 v[46:49], v[24:27], v[196:199], 0
	v_mfma_f32_16x16x32_bf16 v[16:19], v[16:19], v[244:247], 0
	v_mfma_f32_16x16x32_bf16 v[8:11], v[20:23], v[170:173], v[8:11]
	v_mfma_f32_16x16x32_bf16 v[12:15], v[24:27], v[166:169], 0
	v_mfma_f32_16x16x32_bf16 v[54:57], v[28:31], v[210:213], v[46:49]
	v_mfma_f32_16x16x32_bf16 v[16:19], v[20:23], v[248:251], v[16:19]
	v_mfma_f32_16x16x32_bf16 v[20:23], v[24:27], v[244:247], 0
	v_mfma_f32_16x16x32_bf16 v[12:15], v[28:31], v[170:173], v[12:15]
	v_mfma_f32_16x16x32_bf16 v[20:23], v[28:31], v[248:251], v[20:23]
	s_setprio 0
	s_barrier
	s_add_i32 s0, 0, 0x18000
	v_add_u32_e32 v32, s0, v205
	s_add_i32 s54, 0, 0x1c000
	ds_read_b128 v[24:27], v32
	ds_read_b128 v[28:31], v32 offset:1024
	ds_read_b128 v[38:41], v32 offset:2048
	ds_read_b128 v[42:45], v32 offset:3072
	v_add_u32_e32 v32, s54, v205
	ds_read_b128 v[166:169], v32
	ds_read_b128 v[170:173], v32 offset:1024
	ds_read_b128 v[174:177], v32 offset:2048
	ds_read_b128 v[178:181], v32 offset:3072
	s_add_u32 s76, s76, 0x40000
	s_addc_u32 s77, s77, 0
	s_mov_b32 m0, s40
	v_lshl_add_u64 v[218:219], s[76:77], 0, v[184:185]
	ds_read_b128 v[46:49], v209 offset:32768
	ds_read_b128 v[50:53], v209 offset:33792
	ds_read_b128 v[86:89], v209 offset:34816
	ds_read_b128 v[90:93], v209 offset:35840
	ds_read_b128 v[196:199], v209 offset:36864
	ds_read_b128 v[210:213], v209 offset:37888
	ds_read_b128 v[244:247], v209 offset:38912
	ds_read_b128 v[248:251], v209 offset:39936
	global_load_lds_dwordx4 v[218:219], off
	v_lshl_add_u64 v[218:219], s[76:77], 0, v[186:187]
	s_mov_b32 m0, s41
	s_nop 0
	global_load_lds_dwordx4 v[218:219], off
	s_waitcnt vmcnt(8)
	s_waitcnt lgkmcnt(0)
	s_barrier
	s_setprio 1
	s_waitcnt lgkmcnt(0)
	v_mfma_f32_16x16x32_bf16 v[162:165], v[24:27], v[46:49], v[162:165]
	v_mfma_f32_16x16x32_bf16 v[158:161], v[38:41], v[46:49], v[158:161]
	v_mfma_f32_16x16x32_bf16 v[146:149], v[24:27], v[86:89], v[146:149]
	v_mfma_f32_16x16x32_bf16 v[142:145], v[38:41], v[86:89], v[142:145]
	v_mfma_f32_16x16x32_bf16 v[130:133], v[24:27], v[196:199], v[130:133]
	v_mfma_f32_16x16x32_bf16 v[126:129], v[38:41], v[196:199], v[126:129]
	v_mfma_f32_16x16x32_bf16 v[114:117], v[24:27], v[244:247], v[114:117]
	v_mfma_f32_16x16x32_bf16 v[110:113], v[38:41], v[244:247], v[110:113]
	v_mfma_f32_16x16x32_bf16 v[162:165], v[28:31], v[50:53], v[162:165]
	v_mfma_f32_16x16x32_bf16 v[158:161], v[42:45], v[50:53], v[158:161]
	v_mfma_f32_16x16x32_bf16 v[146:149], v[28:31], v[90:93], v[146:149]
	v_mfma_f32_16x16x32_bf16 v[142:145], v[42:45], v[90:93], v[142:145]
	v_mfma_f32_16x16x32_bf16 v[130:133], v[28:31], v[210:213], v[130:133]
	v_mfma_f32_16x16x32_bf16 v[126:129], v[42:45], v[210:213], v[126:129]
	v_mfma_f32_16x16x32_bf16 v[114:117], v[28:31], v[248:251], v[114:117]
	v_mfma_f32_16x16x32_bf16 v[110:113], v[42:45], v[248:251], v[110:113]
	s_setprio 0
	s_setprio 1
	v_mfma_f32_16x16x32_bf16 v[154:157], v[166:169], v[46:49], v[154:157]
	v_mfma_f32_16x16x32_bf16 v[46:49], v[174:177], v[46:49], v[150:153]
	v_mfma_f32_16x16x32_bf16 v[150:153], v[178:181], v[50:53], v[46:49]
	v_mfma_f32_16x16x32_bf16 v[46:49], v[166:169], v[86:89], v[138:141]
	v_mfma_f32_16x16x32_bf16 v[138:141], v[170:173], v[90:93], v[46:49]
	v_mfma_f32_16x16x32_bf16 v[46:49], v[174:177], v[86:89], v[134:137]
	v_mfma_f32_16x16x32_bf16 v[134:137], v[178:181], v[90:93], v[46:49]
	v_mfma_f32_16x16x32_bf16 v[46:49], v[166:169], v[196:199], v[122:125]
	v_mfma_f32_16x16x32_bf16 v[122:125], v[170:173], v[210:213], v[46:49]
	v_mfma_f32_16x16x32_bf16 v[46:49], v[174:177], v[196:199], v[118:121]
	v_mfma_f32_16x16x32_bf16 v[118:121], v[178:181], v[210:213], v[46:49]
	v_mfma_f32_16x16x32_bf16 v[46:49], v[166:169], v[244:247], v[106:109]
	v_mfma_f32_16x16x32_bf16 v[106:109], v[170:173], v[248:251], v[46:49]
	v_mfma_f32_16x16x32_bf16 v[46:49], v[174:177], v[244:247], v[102:105]
	v_mfma_f32_16x16x32_bf16 v[154:157], v[170:173], v[50:53], v[154:157]
	v_mfma_f32_16x16x32_bf16 v[102:105], v[178:181], v[248:251], v[46:49]
	s_setprio 0
	s_barrier
	s_add_i32 s0, s0, s95
	s_nop 2
	v_lshl_add_u64 v[46:47], v[202:203], 0, s[68:69]
	s_mov_b32 m0, s0
	ds_read_b128 v[86:89], v209 offset:49152
	ds_read_b128 v[196:199], v209 offset:50176
	ds_read_b128 v[210:213], v209 offset:51200
	ds_read_b128 v[244:247], v209 offset:52224
	ds_read_b128 v[248:251], v209 offset:53248
	ds_read_b128 v[228:231], v209 offset:54272
	ds_read_b128 v[232:235], v209 offset:55296
	ds_read_b128 v[218:221], v209 offset:56320
	global_load_lds_dwordx4 v[46:47], off
	s_add_i32 m0, s0, 0x2000
	s_add_u32 s34, s34, 0x40080
	v_lshl_add_u64 v[46:47], v[214:215], 0, s[68:69]
	s_addc_u32 s35, s35, 0
	s_add_i32 s0, s54, s95
	global_load_lds_dwordx4 v[46:47], off
	v_lshl_add_u64 v[46:47], s[34:35], 0, v[182:183]
	s_mov_b32 m0, s0
	s_nop 0
	global_load_lds_dwordx4 v[46:47], off
	v_lshl_add_u64 v[46:47], s[34:35], 0, v[34:35]
	s_add_i32 m0, s0, 0x2000
	s_nop 0
	global_load_lds_dwordx4 v[46:47], off
	v_lshl_add_u64 v[46:47], v[222:223], 0, s[68:69]
	s_mov_b32 m0, s43
	s_nop 0
	global_load_lds_dwordx4 v[46:47], off
	v_lshl_add_u64 v[46:47], v[236:237], 0, s[68:69]
	s_mov_b32 m0, s83
	s_nop 0
	global_load_lds_dwordx4 v[46:47], off
	s_waitcnt vmcnt(8)
	s_waitcnt lgkmcnt(0)
	s_barrier
	s_setprio 1
	s_waitcnt lgkmcnt(0)
	v_mfma_f32_16x16x32_bf16 v[46:49], v[24:27], v[86:89], v[98:101]
	v_mfma_f32_16x16x32_bf16 v[98:101], v[28:31], v[196:199], v[46:49]
	v_mfma_f32_16x16x32_bf16 v[46:49], v[38:41], v[86:89], v[94:97]
	v_mfma_f32_16x16x32_bf16 v[94:97], v[42:45], v[196:199], v[46:49]
	v_mfma_f32_16x16x32_bf16 v[46:49], v[24:27], v[210:213], v[82:85]
	v_mfma_f32_16x16x32_bf16 v[82:85], v[28:31], v[244:247], v[46:49]
	v_mfma_f32_16x16x32_bf16 v[46:49], v[38:41], v[210:213], v[78:81]
	v_mfma_f32_16x16x32_bf16 v[78:81], v[42:45], v[244:247], v[46:49]
	v_mfma_f32_16x16x32_bf16 v[46:49], v[24:27], v[248:251], v[66:69]
	v_mfma_f32_16x16x32_bf16 v[0:3], v[24:27], v[232:235], v[0:3]
	v_mfma_f32_16x16x32_bf16 v[66:69], v[28:31], v[228:231], v[46:49]
	v_mfma_f32_16x16x32_bf16 v[46:49], v[38:41], v[248:251], v[62:65]
	v_mfma_f32_16x16x32_bf16 v[50:53], v[28:31], v[218:221], v[0:3]
	v_mfma_f32_16x16x32_bf16 v[0:3], v[38:41], v[232:235], v[4:7]
	v_mfma_f32_16x16x32_bf16 v[62:65], v[42:45], v[228:231], v[46:49]
	v_mfma_f32_16x16x32_bf16 v[46:49], v[42:45], v[218:221], v[0:3]
	s_setprio 0
	s_setprio 1
	v_mfma_f32_16x16x32_bf16 v[0:3], v[166:169], v[86:89], v[8:11]
	v_mfma_f32_16x16x32_bf16 v[90:93], v[170:173], v[196:199], v[0:3]
	v_mfma_f32_16x16x32_bf16 v[0:3], v[174:177], v[86:89], v[12:15]
	v_mfma_f32_16x16x32_bf16 v[86:89], v[178:181], v[196:199], v[0:3]
	v_mfma_f32_16x16x32_bf16 v[0:3], v[166:169], v[210:213], v[74:77]
	v_mfma_f32_16x16x32_bf16 v[74:77], v[170:173], v[244:247], v[0:3]
	v_mfma_f32_16x16x32_bf16 v[0:3], v[174:177], v[210:213], v[70:73]
	v_mfma_f32_16x16x32_bf16 v[70:73], v[178:181], v[244:247], v[0:3]
	v_mfma_f32_16x16x32_bf16 v[0:3], v[166:169], v[248:251], v[58:61]
	v_mfma_f32_16x16x32_bf16 v[58:61], v[170:173], v[228:231], v[0:3]
	v_mfma_f32_16x16x32_bf16 v[0:3], v[174:177], v[248:251], v[54:57]
	v_mfma_f32_16x16x32_bf16 v[54:57], v[178:181], v[228:231], v[0:3]
	v_mfma_f32_16x16x32_bf16 v[0:3], v[166:169], v[232:235], v[16:19]
	v_mfma_f32_16x16x32_bf16 v[42:45], v[170:173], v[218:221], v[0:3]
	v_mfma_f32_16x16x32_bf16 v[0:3], v[174:177], v[232:235], v[20:23]
	v_mfma_f32_16x16x32_bf16 v[38:41], v[178:181], v[218:221], v[0:3]
	s_setprio 0
	s_barrier
	s_cmp_gt_u32 s89, 13
	s_mov_b32 s89, s92
	s_cbranch_scc1 .LBB0_343
	s_branch .LBB0_316

.LBB0_480:
	s_ashr_i32 s21, s20, 31
	s_lshl_b64 s[34:35], s[20:21], 19
	s_add_u32 s36, s26, s34
	s_addc_u32 s37, s27, s35
	s_and_b64 s[34:35], exec, s[12:13]
	s_cselect_b32 s21, s11, s37
	s_cselect_b32 s66, s10, s36
	s_ashr_i32 s23, s22, 31
	s_lshl_b64 s[34:35], s[22:23], 19
	s_add_u32 s38, s28, s34
	s_addc_u32 s39, s29, s35
	s_and_b64 s[34:35], exec, s[12:13]
	s_cselect_b32 s23, s9, s39
	s_cselect_b32 s74, s8, s38
	s_lshl_b32 s34, s20, 4
	s_ashr_i32 s35, s34, 31
	s_cmp_lt_i32 s20, 64
	s_cselect_b32 s75, 32, 0x100
	s_lshl_b64 s[34:35], s[34:35], 2
	s_add_u32 s40, s61, s34
	s_addc_u32 s41, s55, s35
	s_mov_b32 s76, 0
.Lpeel_b:
	s_mov_b64 s[34:35], -1
	s_or_b32 s92, s76, 1
	s_lshl_b64 s[42:43], s[92:93], 7
	s_add_u32 s0, s10, s42
	s_addc_u32 s48, s11, s43
	s_add_i32 s92, s76, 2
	s_lshl_b64 s[46:47], s[92:93], 7
	s_add_u32 s49, s10, s46
	s_addc_u32 s54, s11, s47
	s_and_b64 s[42:43], s[34:35], exec
	s_cselect_b32 s43, s54, s21
	s_cselect_b32 s42, s49, s66
	s_add_u32 s46, s8, s46
	s_addc_u32 s47, s9, s47
	s_and_b64 s[34:35], s[34:35], exec
	s_cselect_b32 s35, s47, s23
	s_cselect_b32 s34, s46, s74
	s_add_i32 s49, 0, 0x10000
	s_add_i32 s54, 0, 0x14000
	v_add_u32_e32 v12, s49, v205
	v_add_u32_e32 v28, s54, v205
	ds_read_b128 v[0:3], v12
	ds_read_b128 v[4:7], v12 offset:1024
	ds_read_b128 v[8:11], v12 offset:2048
	ds_read_b128 v[12:15], v12 offset:3072
	ds_read_b128 v[16:19], v28
	ds_read_b128 v[20:23], v28 offset:1024
	ds_read_b128 v[24:27], v28 offset:2048
	ds_read_b128 v[28:31], v28 offset:3072
	s_add_u32 s46, s0, 0x40000
	s_addc_u32 s47, s48, 0
	v_lshl_add_u64 v[202:203], s[46:47], 0, v[184:185]
	s_add_i32 m0, s53, 0xc000
	ds_read_b128 v[166:169], v209
	ds_read_b128 v[170:173], v209 offset:1024
	ds_read_b128 v[174:177], v209 offset:2048
	ds_read_b128 v[178:181], v209 offset:3072
	ds_read_b128 v[196:199], v209 offset:4096
	ds_read_b128 v[210:213], v209 offset:5120
	ds_read_b128 v[218:221], v209 offset:6144
	ds_read_b128 v[228:231], v209 offset:7168
	global_load_lds_dwordx4 v[202:203], off
	v_lshl_add_u64 v[202:203], s[46:47], 0, v[186:187]
	s_add_i32 m0, s53, 0xe000
	s_nop 0
	global_load_lds_dwordx4 v[202:203], off
	s_waitcnt vmcnt(8)
	s_waitcnt lgkmcnt(0)
	s_barrier
	s_setprio 1
	s_waitcnt lgkmcnt(0)
	v_mfma_f32_16x16x32_bf16 v[162:165], v[0:3], v[166:169], 0
	v_mfma_f32_16x16x32_bf16 v[158:161], v[8:11], v[166:169], 0
	v_mfma_f32_16x16x32_bf16 v[146:149], v[0:3], v[174:177], 0
	v_mfma_f32_16x16x32_bf16 v[142:145], v[8:11], v[174:177], 0
	v_mfma_f32_16x16x32_bf16 v[130:133], v[0:3], v[196:199], 0
	v_mfma_f32_16x16x32_bf16 v[126:129], v[8:11], v[196:199], 0
	v_mfma_f32_16x16x32_bf16 v[114:117], v[0:3], v[218:221], 0
	v_mfma_f32_16x16x32_bf16 v[110:113], v[8:11], v[218:221], 0
	v_mfma_f32_16x16x32_bf16 v[162:165], v[4:7], v[170:173], v[162:165]
	v_mfma_f32_16x16x32_bf16 v[158:161], v[12:15], v[170:173], v[158:161]
	v_mfma_f32_16x16x32_bf16 v[146:149], v[4:7], v[178:181], v[146:149]
	v_mfma_f32_16x16x32_bf16 v[142:145], v[12:15], v[178:181], v[142:145]
	v_mfma_f32_16x16x32_bf16 v[130:133], v[4:7], v[210:213], v[130:133]
	v_mfma_f32_16x16x32_bf16 v[126:129], v[12:15], v[210:213], v[126:129]
	v_mfma_f32_16x16x32_bf16 v[114:117], v[4:7], v[228:231], v[114:117]
	v_mfma_f32_16x16x32_bf16 v[110:113], v[12:15], v[228:231], v[110:113]
	s_setprio 0
	s_setprio 1
	v_mfma_f32_16x16x32_bf16 v[154:157], v[16:19], v[166:169], 0
	v_mfma_f32_16x16x32_bf16 v[150:153], v[24:27], v[166:169], 0
	v_mfma_f32_16x16x32_bf16 v[138:141], v[16:19], v[174:177], 0
	v_mfma_f32_16x16x32_bf16 v[134:137], v[24:27], v[174:177], 0
	v_mfma_f32_16x16x32_bf16 v[122:125], v[16:19], v[196:199], 0
	v_mfma_f32_16x16x32_bf16 v[118:121], v[24:27], v[196:199], 0
	v_mfma_f32_16x16x32_bf16 v[106:109], v[16:19], v[218:221], 0
	v_mfma_f32_16x16x32_bf16 v[102:105], v[24:27], v[218:221], 0
	v_mfma_f32_16x16x32_bf16 v[154:157], v[20:23], v[170:173], v[154:157]
	v_mfma_f32_16x16x32_bf16 v[150:153], v[28:31], v[170:173], v[150:153]
	v_mfma_f32_16x16x32_bf16 v[138:141], v[20:23], v[178:181], v[138:141]
	v_mfma_f32_16x16x32_bf16 v[134:137], v[28:31], v[178:181], v[134:137]
	v_mfma_f32_16x16x32_bf16 v[122:125], v[20:23], v[210:213], v[122:125]
	v_mfma_f32_16x16x32_bf16 v[118:121], v[28:31], v[210:213], v[118:121]
	v_mfma_f32_16x16x32_bf16 v[106:109], v[20:23], v[228:231], v[106:109]
	v_mfma_f32_16x16x32_bf16 v[102:105], v[28:31], v[228:231], v[102:105]
	s_setprio 0
	s_barrier
	s_add_i32 s0, s49, s52
	v_lshl_add_u64 v[202:203], s[34:35], 0, v[182:183]
	s_mov_b32 m0, s0
	ds_read_b128 v[166:169], v209 offset:16384
	ds_read_b128 v[170:173], v209 offset:17408
	ds_read_b128 v[174:177], v209 offset:18432
	ds_read_b128 v[178:181], v209 offset:19456
	ds_read_b128 v[196:199], v209 offset:20480
	ds_read_b128 v[210:213], v209 offset:21504
	ds_read_b128 v[218:221], v209 offset:22528
	ds_read_b128 v[228:231], v209 offset:23552
	global_load_lds_dwordx4 v[202:203], off
	s_add_i32 m0, s0, 0x2000
	s_add_u32 s46, s34, 0x40000
	v_lshl_add_u64 v[214:215], s[34:35], 0, v[34:35]
	s_addc_u32 s47, s35, 0
	s_add_i32 s0, s54, s52
	global_load_lds_dwordx4 v[214:215], off
	v_lshl_add_u64 v[222:223], s[46:47], 0, v[182:183]
	s_mov_b32 m0, s0
	v_lshl_add_u64 v[236:237], s[42:43], 0, v[186:187]
	global_load_lds_dwordx4 v[222:223], off
	v_lshl_add_u64 v[222:223], s[46:47], 0, v[34:35]
	s_add_i32 m0, s0, 0x2000
	s_nop 0
	global_load_lds_dwordx4 v[222:223], off
	v_lshl_add_u64 v[222:223], s[42:43], 0, v[184:185]
	s_mov_b32 m0, s53
	s_nop 0
	global_load_lds_dwordx4 v[222:223], off
	s_mov_b32 m0, s56
	s_nop 0
	global_load_lds_dwordx4 v[236:237], off
	s_waitcnt vmcnt(8)
	s_waitcnt lgkmcnt(0)
	s_barrier
	s_setprio 1
	s_waitcnt lgkmcnt(0)
	v_mfma_f32_16x16x32_bf16 v[98:101], v[0:3], v[166:169], 0
	v_mfma_f32_16x16x32_bf16 v[94:97], v[8:11], v[166:169], 0
	v_mfma_f32_16x16x32_bf16 v[82:85], v[0:3], v[174:177], 0
	v_mfma_f32_16x16x32_bf16 v[78:81], v[8:11], v[174:177], 0
	v_mfma_f32_16x16x32_bf16 v[66:69], v[0:3], v[196:199], 0
	v_mfma_f32_16x16x32_bf16 v[62:65], v[8:11], v[196:199], 0
	v_mfma_f32_16x16x32_bf16 v[0:3], v[0:3], v[218:221], 0
	v_mfma_f32_16x16x32_bf16 v[98:101], v[4:7], v[170:173], v[98:101]
	v_mfma_f32_16x16x32_bf16 v[94:97], v[12:15], v[170:173], v[94:97]
	v_mfma_f32_16x16x32_bf16 v[82:85], v[4:7], v[178:181], v[82:85]
	v_mfma_f32_16x16x32_bf16 v[78:81], v[12:15], v[178:181], v[78:81]
	v_mfma_f32_16x16x32_bf16 v[66:69], v[4:7], v[210:213], v[66:69]
	v_mfma_f32_16x16x32_bf16 v[62:65], v[12:15], v[210:213], v[62:65]
	v_mfma_f32_16x16x32_bf16 v[0:3], v[4:7], v[228:231], v[0:3]
	v_mfma_f32_16x16x32_bf16 v[4:7], v[8:11], v[218:221], 0
	v_mfma_f32_16x16x32_bf16 v[4:7], v[12:15], v[228:231], v[4:7]
	s_setprio 0
	s_setprio 1
	v_mfma_f32_16x16x32_bf16 v[46:49], v[16:19], v[174:177], 0
	v_mfma_f32_16x16x32_bf16 v[74:77], v[20:23], v[178:181], v[46:49]
	v_mfma_f32_16x16x32_bf16 v[46:49], v[24:27], v[174:177], 0
	v_mfma_f32_16x16x32_bf16 v[70:73], v[28:31], v[178:181], v[46:49]
	v_mfma_f32_16x16x32_bf16 v[46:49], v[16:19], v[196:199], 0
	v_mfma_f32_16x16x32_bf16 v[8:11], v[16:19], v[166:169], 0
	v_mfma_f32_16x16x32_bf16 v[58:61], v[20:23], v[210:213], v[46:49]
	v_mfma_f32_16x16x32_bf16 v[46:49], v[24:27], v[196:199], 0
	v_mfma_f32_16x16x32_bf16 v[16:19], v[16:19], v[218:221], 0
	v_mfma_f32_16x16x32_bf16 v[8:11], v[20:23], v[170:173], v[8:11]
	v_mfma_f32_16x16x32_bf16 v[12:15], v[24:27], v[166:169], 0
	v_mfma_f32_16x16x32_bf16 v[54:57], v[28:31], v[210:213], v[46:49]
	v_mfma_f32_16x16x32_bf16 v[16:19], v[20:23], v[228:231], v[16:19]
	v_mfma_f32_16x16x32_bf16 v[20:23], v[24:27], v[218:221], 0
	v_mfma_f32_16x16x32_bf16 v[12:15], v[28:31], v[170:173], v[12:15]
	v_mfma_f32_16x16x32_bf16 v[20:23], v[28:31], v[228:231], v[20:23]
	s_setprio 0
	s_barrier
	s_add_i32 s0, 0, 0x18000
	v_add_u32_e32 v32, s0, v205
	s_add_i32 s46, 0, 0x1c000
	ds_read_b128 v[24:27], v32
	ds_read_b128 v[28:31], v32 offset:1024
	ds_read_b128 v[38:41], v32 offset:2048
	ds_read_b128 v[42:45], v32 offset:3072
	v_add_u32_e32 v32, s46, v205
	ds_read_b128 v[166:169], v32
	ds_read_b128 v[170:173], v32 offset:1024
	ds_read_b128 v[174:177], v32 offset:2048
	ds_read_b128 v[178:181], v32 offset:3072
	s_add_u32 s42, s42, 0x40000
	s_addc_u32 s43, s43, 0
	s_mov_b32 m0, s57
	v_lshl_add_u64 v[232:233], s[42:43], 0, v[184:185]
	ds_read_b128 v[46:49], v209 offset:32768
	ds_read_b128 v[50:53], v209 offset:33792
	ds_read_b128 v[86:89], v209 offset:34816
	ds_read_b128 v[90:93], v209 offset:35840
	ds_read_b128 v[196:199], v209 offset:36864
	ds_read_b128 v[210:213], v209 offset:37888
	ds_read_b128 v[218:221], v209 offset:38912
	ds_read_b128 v[228:231], v209 offset:39936
	global_load_lds_dwordx4 v[232:233], off
	v_lshl_add_u64 v[232:233], s[42:43], 0, v[186:187]
	s_mov_b32 m0, s62
	s_nop 0
	global_load_lds_dwordx4 v[232:233], off
	s_waitcnt vmcnt(8)
	s_waitcnt lgkmcnt(0)
	s_barrier
	s_setprio 1
	s_waitcnt lgkmcnt(0)
	v_mfma_f32_16x16x32_bf16 v[162:165], v[24:27], v[46:49], v[162:165]
	v_mfma_f32_16x16x32_bf16 v[158:161], v[38:41], v[46:49], v[158:161]
	v_mfma_f32_16x16x32_bf16 v[146:149], v[24:27], v[86:89], v[146:149]
	v_mfma_f32_16x16x32_bf16 v[142:145], v[38:41], v[86:89], v[142:145]
	v_mfma_f32_16x16x32_bf16 v[130:133], v[24:27], v[196:199], v[130:133]
	v_mfma_f32_16x16x32_bf16 v[126:129], v[38:41], v[196:199], v[126:129]
	v_mfma_f32_16x16x32_bf16 v[114:117], v[24:27], v[218:221], v[114:117]
	v_mfma_f32_16x16x32_bf16 v[110:113], v[38:41], v[218:221], v[110:113]
	v_mfma_f32_16x16x32_bf16 v[162:165], v[28:31], v[50:53], v[162:165]
	v_mfma_f32_16x16x32_bf16 v[158:161], v[42:45], v[50:53], v[158:161]
	v_mfma_f32_16x16x32_bf16 v[146:149], v[28:31], v[90:93], v[146:149]
	v_mfma_f32_16x16x32_bf16 v[142:145], v[42:45], v[90:93], v[142:145]
	v_mfma_f32_16x16x32_bf16 v[130:133], v[28:31], v[210:213], v[130:133]
	v_mfma_f32_16x16x32_bf16 v[126:129], v[42:45], v[210:213], v[126:129]
	v_mfma_f32_16x16x32_bf16 v[114:117], v[28:31], v[228:231], v[114:117]
	v_mfma_f32_16x16x32_bf16 v[110:113], v[42:45], v[228:231], v[110:113]
	s_setprio 0
	s_setprio 1
	v_mfma_f32_16x16x32_bf16 v[154:157], v[166:169], v[46:49], v[154:157]
	v_mfma_f32_16x16x32_bf16 v[46:49], v[174:177], v[46:49], v[150:153]
	v_mfma_f32_16x16x32_bf16 v[150:153], v[178:181], v[50:53], v[46:49]
	v_mfma_f32_16x16x32_bf16 v[46:49], v[166:169], v[86:89], v[138:141]
	v_mfma_f32_16x16x32_bf16 v[138:141], v[170:173], v[90:93], v[46:49]
	v_mfma_f32_16x16x32_bf16 v[46:49], v[174:177], v[86:89], v[134:137]
	v_mfma_f32_16x16x32_bf16 v[134:137], v[178:181], v[90:93], v[46:49]
	v_mfma_f32_16x16x32_bf16 v[46:49], v[166:169], v[196:199], v[122:125]
	v_mfma_f32_16x16x32_bf16 v[122:125], v[170:173], v[210:213], v[46:49]
	v_mfma_f32_16x16x32_bf16 v[46:49], v[174:177], v[196:199], v[118:121]
	v_mfma_f32_16x16x32_bf16 v[118:121], v[178:181], v[210:213], v[46:49]
	v_mfma_f32_16x16x32_bf16 v[46:49], v[166:169], v[218:221], v[106:109]
	v_mfma_f32_16x16x32_bf16 v[106:109], v[170:173], v[228:231], v[46:49]
	v_mfma_f32_16x16x32_bf16 v[46:49], v[174:177], v[218:221], v[102:105]
	v_mfma_f32_16x16x32_bf16 v[154:157], v[170:173], v[50:53], v[154:157]
	v_mfma_f32_16x16x32_bf16 v[102:105], v[178:181], v[228:231], v[46:49]
	s_setprio 0
	s_barrier
	s_add_i32 s0, s0, s52
	s_nop 2
	v_lshl_add_u64 v[46:47], v[202:203], 0, s[68:69]
	s_mov_b32 m0, s0
	ds_read_b128 v[86:89], v209 offset:49152
	ds_read_b128 v[196:199], v209 offset:50176
	ds_read_b128 v[210:213], v209 offset:51200
	ds_read_b128 v[218:221], v209 offset:52224
	ds_read_b128 v[228:231], v209 offset:53248
	ds_read_b128 v[232:235], v209 offset:54272
	ds_read_b128 v[244:247], v209 offset:55296
	ds_read_b128 v[248:251], v209 offset:56320
	global_load_lds_dwordx4 v[46:47], off
	s_add_i32 m0, s0, 0x2000
	s_add_u32 s34, s34, 0x40080
	v_lshl_add_u64 v[46:47], v[214:215], 0, s[68:69]
	s_addc_u32 s35, s35, 0
	s_add_i32 s0, s46, s52
	global_load_lds_dwordx4 v[46:47], off
	v_lshl_add_u64 v[46:47], s[34:35], 0, v[182:183]
	s_mov_b32 m0, s0
	s_nop 0
	global_load_lds_dwordx4 v[46:47], off
	v_lshl_add_u64 v[46:47], s[34:35], 0, v[34:35]
	s_add_i32 m0, s0, 0x2000
	s_nop 0
	global_load_lds_dwordx4 v[46:47], off
	v_lshl_add_u64 v[46:47], v[222:223], 0, s[68:69]
	s_mov_b32 m0, s64
	s_nop 0
	global_load_lds_dwordx4 v[46:47], off
	v_lshl_add_u64 v[46:47], v[236:237], 0, s[68:69]
	s_mov_b32 m0, s65
	s_nop 0
	global_load_lds_dwordx4 v[46:47], off
	s_waitcnt vmcnt(8)
	s_waitcnt lgkmcnt(0)
	s_barrier
	s_setprio 1
	s_waitcnt lgkmcnt(0)
	v_mfma_f32_16x16x32_bf16 v[46:49], v[24:27], v[86:89], v[98:101]
	v_mfma_f32_16x16x32_bf16 v[98:101], v[28:31], v[196:199], v[46:49]
	v_mfma_f32_16x16x32_bf16 v[46:49], v[38:41], v[86:89], v[94:97]
	v_mfma_f32_16x16x32_bf16 v[94:97], v[42:45], v[196:199], v[46:49]
	v_mfma_f32_16x16x32_bf16 v[46:49], v[24:27], v[210:213], v[82:85]
	v_mfma_f32_16x16x32_bf16 v[82:85], v[28:31], v[218:221], v[46:49]
	v_mfma_f32_16x16x32_bf16 v[46:49], v[38:41], v[210:213], v[78:81]
	v_mfma_f32_16x16x32_bf16 v[78:81], v[42:45], v[218:221], v[46:49]
	v_mfma_f32_16x16x32_bf16 v[46:49], v[24:27], v[228:231], v[66:69]
	v_mfma_f32_16x16x32_bf16 v[0:3], v[24:27], v[244:247], v[0:3]
	v_mfma_f32_16x16x32_bf16 v[66:69], v[28:31], v[232:235], v[46:49]
	v_mfma_f32_16x16x32_bf16 v[46:49], v[38:41], v[228:231], v[62:65]
	v_mfma_f32_16x16x32_bf16 v[50:53], v[28:31], v[248:251], v[0:3]
	v_mfma_f32_16x16x32_bf16 v[0:3], v[38:41], v[244:247], v[4:7]
	v_mfma_f32_16x16x32_bf16 v[62:65], v[42:45], v[232:235], v[46:49]
	v_mfma_f32_16x16x32_bf16 v[46:49], v[42:45], v[248:251], v[0:3]
	s_setprio 0
	s_setprio 1
	v_mfma_f32_16x16x32_bf16 v[0:3], v[166:169], v[86:89], v[8:11]
	v_mfma_f32_16x16x32_bf16 v[90:93], v[170:173], v[196:199], v[0:3]
	v_mfma_f32_16x16x32_bf16 v[0:3], v[174:177], v[86:89], v[12:15]
	v_mfma_f32_16x16x32_bf16 v[86:89], v[178:181], v[196:199], v[0:3]
	v_mfma_f32_16x16x32_bf16 v[0:3], v[166:169], v[210:213], v[74:77]
	v_mfma_f32_16x16x32_bf16 v[74:77], v[170:173], v[218:221], v[0:3]
	v_mfma_f32_16x16x32_bf16 v[0:3], v[174:177], v[210:213], v[70:73]
	v_mfma_f32_16x16x32_bf16 v[70:73], v[178:181], v[218:221], v[0:3]
	v_mfma_f32_16x16x32_bf16 v[0:3], v[166:169], v[228:231], v[58:61]
	v_mfma_f32_16x16x32_bf16 v[58:61], v[170:173], v[232:235], v[0:3]
	v_mfma_f32_16x16x32_bf16 v[0:3], v[174:177], v[228:231], v[54:57]
	v_mfma_f32_16x16x32_bf16 v[54:57], v[178:181], v[232:235], v[0:3]
	v_mfma_f32_16x16x32_bf16 v[0:3], v[166:169], v[244:247], v[16:19]
	v_mfma_f32_16x16x32_bf16 v[42:45], v[170:173], v[248:251], v[0:3]
	v_mfma_f32_16x16x32_bf16 v[0:3], v[174:177], v[244:247], v[20:23]
	v_mfma_f32_16x16x32_bf16 v[38:41], v[178:181], v[248:251], v[0:3]
	s_setprio 0
	s_barrier
	s_cmp_gt_u32 s76, 13
	s_mov_b32 s76, s92
	s_cbranch_scc1 .LBB0_515
	s_branch .LBB0_483

.LBB0_902:
	s_lshl_b32 s0, s73, 2
	s_lshl_b32 s38, s72, 4
	s_add_i32 s0, s0, s71
	s_add_i32 s10, s0, s38
	s_ashr_i32 s11, s10, 31
	s_lshl_b64 s[10:11], s[10:11], 16
	v_lshl_add_u64 v[210:211], v[204:205], 0, s[10:11]
	s_mov_b64 s[10:11], 0x1000
	v_lshl_add_u64 v[212:213], v[210:211], 0, s[10:11]
	s_mov_b64 s[10:11], 0x10000
	v_lshl_add_u64 v[214:215], v[210:211], 0, s[10:11]
	s_mov_b64 s[10:11], 0x11000
	v_lshl_add_u64 v[218:219], v[210:211], 0, s[10:11]
	global_load_dwordx4 v[190:193], v[210:211], off
	global_load_dwordx4 v[182:185], v[210:211], off offset:1024
	global_load_dwordx4 v[174:177], v[210:211], off offset:2048
	global_load_dwordx4 v[166:169], v[210:211], off offset:3072
	global_load_dwordx4 v[158:161], v[212:213], off
	global_load_dwordx4 v[150:153], v[212:213], off offset:1024
	global_load_dwordx4 v[142:145], v[212:213], off offset:2048
	global_load_dwordx4 v[134:137], v[212:213], off offset:3072
	s_cmp_gt_i32 s71, 2
	s_cbranch_scc1 .Lwo_eq3
	global_load_dwordx4 v[194:197], v[214:215], off
	global_load_dwordx4 v[186:189], v[214:215], off offset:1024
	global_load_dwordx4 v[178:181], v[214:215], off offset:2048
	global_load_dwordx4 v[170:173], v[214:215], off offset:3072
	global_load_dwordx4 v[162:165], v[218:219], off
	global_load_dwordx4 v[154:157], v[218:219], off offset:1024
	global_load_dwordx4 v[146:149], v[218:219], off offset:2048
	global_load_dwordx4 v[138:141], v[218:219], off offset:3072
	s_waitcnt vmcnt(0)
	v_cvt_f32_ubyte0_e32 v210, v190
	v_cvt_f32_ubyte1_e32 v211, v190
	v_cvt_f32_ubyte2_e32 v212, v190
	v_cvt_f32_ubyte3_e32 v213, v190
	v_cvt_f32_ubyte0_e32 v214, v194
	v_cvt_f32_ubyte1_e32 v215, v194
	v_cvt_f32_ubyte2_e32 v218, v194
	v_cvt_f32_ubyte3_e32 v219, v194
	v_rcp_iflag_f32_e32 v214, v214
	v_rcp_iflag_f32_e32 v215, v215
	v_rcp_iflag_f32_e32 v218, v218
	v_rcp_iflag_f32_e32 v219, v219
	v_mul_f32_e32 v210, v214, v210
	v_mul_f32_e32 v211, v215, v211
	v_mul_f32_e32 v212, v218, v212
	v_mul_f32_e32 v213, v219, v213
	v_pk_mul_f32 v[130:131], v[130:131], v[210:211]
	v_pk_mul_f32 v[132:133], v[132:133], v[212:213]
	v_cvt_f32_ubyte0_e32 v210, v191
	v_cvt_f32_ubyte1_e32 v211, v191
	v_cvt_f32_ubyte2_e32 v212, v191
	v_cvt_f32_ubyte3_e32 v213, v191
	v_cvt_f32_ubyte0_e32 v214, v195
	v_cvt_f32_ubyte1_e32 v215, v195
	v_cvt_f32_ubyte2_e32 v218, v195
	v_cvt_f32_ubyte3_e32 v219, v195
	v_rcp_iflag_f32_e32 v214, v214
	v_rcp_iflag_f32_e32 v215, v215
	v_rcp_iflag_f32_e32 v218, v218
	v_rcp_iflag_f32_e32 v219, v219
	v_mul_f32_e32 v210, v214, v210
	v_mul_f32_e32 v211, v215, v211
	v_mul_f32_e32 v212, v218, v212
	v_mul_f32_e32 v213, v219, v213
	v_pk_mul_f32 v[126:127], v[126:127], v[210:211]
	v_pk_mul_f32 v[128:129], v[128:129], v[212:213]
	v_cvt_f32_ubyte0_e32 v210, v192
	v_cvt_f32_ubyte1_e32 v211, v192
	v_cvt_f32_ubyte2_e32 v212, v192
	v_cvt_f32_ubyte3_e32 v213, v192
	v_cvt_f32_ubyte0_e32 v214, v196
	v_cvt_f32_ubyte1_e32 v215, v196
	v_cvt_f32_ubyte2_e32 v218, v196
	v_cvt_f32_ubyte3_e32 v219, v196
	v_rcp_iflag_f32_e32 v214, v214
	v_rcp_iflag_f32_e32 v215, v215
	v_rcp_iflag_f32_e32 v218, v218
	v_rcp_iflag_f32_e32 v219, v219
	v_mul_f32_e32 v210, v214, v210
	v_mul_f32_e32 v211, v215, v211
	v_mul_f32_e32 v212, v218, v212
	v_mul_f32_e32 v213, v219, v213
	v_pk_mul_f32 v[98:99], v[98:99], v[210:211]
	v_pk_mul_f32 v[100:101], v[100:101], v[212:213]
	v_cvt_f32_ubyte0_e32 v210, v193
	v_cvt_f32_ubyte1_e32 v211, v193
	v_cvt_f32_ubyte2_e32 v212, v193
	v_cvt_f32_ubyte3_e32 v213, v193
	v_cvt_f32_ubyte0_e32 v214, v197
	v_cvt_f32_ubyte1_e32 v215, v197
	v_cvt_f32_ubyte2_e32 v218, v197
	v_cvt_f32_ubyte3_e32 v219, v197
	v_rcp_iflag_f32_e32 v214, v214
	v_rcp_iflag_f32_e32 v215, v215
	v_rcp_iflag_f32_e32 v218, v218
	v_rcp_iflag_f32_e32 v219, v219
	v_mul_f32_e32 v210, v214, v210
	v_mul_f32_e32 v211, v215, v211
	v_mul_f32_e32 v212, v218, v212
	v_mul_f32_e32 v213, v219, v213
	v_pk_mul_f32 v[94:95], v[94:95], v[210:211]
	v_pk_mul_f32 v[96:97], v[96:97], v[212:213]
	v_cvt_f32_ubyte0_e32 v210, v182
	v_cvt_f32_ubyte1_e32 v211, v182
	v_cvt_f32_ubyte2_e32 v212, v182
	v_cvt_f32_ubyte3_e32 v213, v182
	v_cvt_f32_ubyte0_e32 v214, v186
	v_cvt_f32_ubyte1_e32 v215, v186
	v_cvt_f32_ubyte2_e32 v218, v186
	v_cvt_f32_ubyte3_e32 v219, v186
	v_rcp_iflag_f32_e32 v214, v214
	v_rcp_iflag_f32_e32 v215, v215
	v_rcp_iflag_f32_e32 v218, v218
	v_rcp_iflag_f32_e32 v219, v219
	v_mul_f32_e32 v210, v214, v210
	v_mul_f32_e32 v211, v215, v211
	v_mul_f32_e32 v212, v218, v212
	v_mul_f32_e32 v213, v219, v213
	v_pk_mul_f32 v[122:123], v[122:123], v[210:211]
	v_pk_mul_f32 v[124:125], v[124:125], v[212:213]
	v_cvt_f32_ubyte0_e32 v210, v183
	v_cvt_f32_ubyte1_e32 v211, v183
	v_cvt_f32_ubyte2_e32 v212, v183
	v_cvt_f32_ubyte3_e32 v213, v183
	v_cvt_f32_ubyte0_e32 v214, v187
	v_cvt_f32_ubyte1_e32 v215, v187
	v_cvt_f32_ubyte2_e32 v218, v187
	v_cvt_f32_ubyte3_e32 v219, v187
	v_rcp_iflag_f32_e32 v214, v214
	v_rcp_iflag_f32_e32 v215, v215
	v_rcp_iflag_f32_e32 v218, v218
	v_rcp_iflag_f32_e32 v219, v219
	v_mul_f32_e32 v210, v214, v210
	v_mul_f32_e32 v211, v215, v211
	v_mul_f32_e32 v212, v218, v212
	v_mul_f32_e32 v213, v219, v213
	v_pk_mul_f32 v[118:119], v[118:119], v[210:211]
	v_pk_mul_f32 v[120:121], v[120:121], v[212:213]
	v_cvt_f32_ubyte0_e32 v210, v184
	v_cvt_f32_ubyte1_e32 v211, v184
	v_cvt_f32_ubyte2_e32 v212, v184
	v_cvt_f32_ubyte3_e32 v213, v184
	v_cvt_f32_ubyte0_e32 v214, v188
	v_cvt_f32_ubyte1_e32 v215, v188
	v_cvt_f32_ubyte2_e32 v218, v188
	v_cvt_f32_ubyte3_e32 v219, v188
	v_rcp_iflag_f32_e32 v214, v214
	v_rcp_iflag_f32_e32 v215, v215
	v_rcp_iflag_f32_e32 v218, v218
	v_rcp_iflag_f32_e32 v219, v219
	v_mul_f32_e32 v210, v214, v210
	v_mul_f32_e32 v211, v215, v211
	v_mul_f32_e32 v212, v218, v212
	v_mul_f32_e32 v213, v219, v213
	v_pk_mul_f32 v[90:91], v[90:91], v[210:211]
	v_pk_mul_f32 v[92:93], v[92:93], v[212:213]
	v_cvt_f32_ubyte0_e32 v210, v185
	v_cvt_f32_ubyte1_e32 v211, v185
	v_cvt_f32_ubyte2_e32 v212, v185
	v_cvt_f32_ubyte3_e32 v213, v185
	v_cvt_f32_ubyte0_e32 v214, v189
	v_cvt_f32_ubyte1_e32 v215, v189
	v_cvt_f32_ubyte2_e32 v218, v189
	v_cvt_f32_ubyte3_e32 v219, v189
	v_rcp_iflag_f32_e32 v214, v214
	v_rcp_iflag_f32_e32 v215, v215
	v_rcp_iflag_f32_e32 v218, v218
	v_rcp_iflag_f32_e32 v219, v219
	v_mul_f32_e32 v210, v214, v210
	v_mul_f32_e32 v211, v215, v211
	v_mul_f32_e32 v212, v218, v212
	v_mul_f32_e32 v213, v219, v213
	v_pk_mul_f32 v[86:87], v[86:87], v[210:211]
	v_pk_mul_f32 v[88:89], v[88:89], v[212:213]
	v_cvt_f32_ubyte0_e32 v210, v174
	v_cvt_f32_ubyte1_e32 v211, v174
	v_cvt_f32_ubyte2_e32 v212, v174
	v_cvt_f32_ubyte3_e32 v213, v174
	v_cvt_f32_ubyte0_e32 v214, v178
	v_cvt_f32_ubyte1_e32 v215, v178
	v_cvt_f32_ubyte2_e32 v218, v178
	v_cvt_f32_ubyte3_e32 v219, v178
	v_rcp_iflag_f32_e32 v214, v214
	v_rcp_iflag_f32_e32 v215, v215
	v_rcp_iflag_f32_e32 v218, v218
	v_rcp_iflag_f32_e32 v219, v219
	v_mul_f32_e32 v210, v214, v210
	v_mul_f32_e32 v211, v215, v211
	v_mul_f32_e32 v212, v218, v212
	v_mul_f32_e32 v213, v219, v213
	v_pk_mul_f32 v[114:115], v[114:115], v[210:211]
	v_pk_mul_f32 v[116:117], v[116:117], v[212:213]
	v_cvt_f32_ubyte0_e32 v210, v175
	v_cvt_f32_ubyte1_e32 v211, v175
	v_cvt_f32_ubyte2_e32 v212, v175
	v_cvt_f32_ubyte3_e32 v213, v175
	v_cvt_f32_ubyte0_e32 v214, v179
	v_cvt_f32_ubyte1_e32 v215, v179
	v_cvt_f32_ubyte2_e32 v218, v179
	v_cvt_f32_ubyte3_e32 v219, v179
	v_rcp_iflag_f32_e32 v214, v214
	v_rcp_iflag_f32_e32 v215, v215
	v_rcp_iflag_f32_e32 v218, v218
	v_rcp_iflag_f32_e32 v219, v219
	v_mul_f32_e32 v210, v214, v210
	v_mul_f32_e32 v211, v215, v211
	v_mul_f32_e32 v212, v218, v212
	v_mul_f32_e32 v213, v219, v213
	v_pk_mul_f32 v[110:111], v[110:111], v[210:211]
	v_pk_mul_f32 v[112:113], v[112:113], v[212:213]
	v_cvt_f32_ubyte0_e32 v210, v176
	v_cvt_f32_ubyte1_e32 v211, v176
	v_cvt_f32_ubyte2_e32 v212, v176
	v_cvt_f32_ubyte3_e32 v213, v176
	v_cvt_f32_ubyte0_e32 v214, v180
	v_cvt_f32_ubyte1_e32 v215, v180
	v_cvt_f32_ubyte2_e32 v218, v180
	v_cvt_f32_ubyte3_e32 v219, v180
	v_rcp_iflag_f32_e32 v214, v214
	v_rcp_iflag_f32_e32 v215, v215
	v_rcp_iflag_f32_e32 v218, v218
	v_rcp_iflag_f32_e32 v219, v219
	v_mul_f32_e32 v210, v214, v210
	v_mul_f32_e32 v211, v215, v211
	v_mul_f32_e32 v212, v218, v212
	v_mul_f32_e32 v213, v219, v213
	v_pk_mul_f32 v[82:83], v[82:83], v[210:211]
	v_pk_mul_f32 v[84:85], v[84:85], v[212:213]
	v_cvt_f32_ubyte0_e32 v210, v177
	v_cvt_f32_ubyte1_e32 v211, v177
	v_cvt_f32_ubyte2_e32 v212, v177
	v_cvt_f32_ubyte3_e32 v213, v177
	v_cvt_f32_ubyte0_e32 v214, v181
	v_cvt_f32_ubyte1_e32 v215, v181
	v_cvt_f32_ubyte2_e32 v218, v181
	v_cvt_f32_ubyte3_e32 v219, v181
	v_rcp_iflag_f32_e32 v214, v214
	v_rcp_iflag_f32_e32 v215, v215
	v_rcp_iflag_f32_e32 v218, v218
	v_rcp_iflag_f32_e32 v219, v219
	v_mul_f32_e32 v210, v214, v210
	v_mul_f32_e32 v211, v215, v211
	v_mul_f32_e32 v212, v218, v212
	v_mul_f32_e32 v213, v219, v213
	v_pk_mul_f32 v[78:79], v[78:79], v[210:211]
	v_pk_mul_f32 v[80:81], v[80:81], v[212:213]
	v_cvt_f32_ubyte0_e32 v210, v166
	v_cvt_f32_ubyte1_e32 v211, v166
	v_cvt_f32_ubyte2_e32 v212, v166
	v_cvt_f32_ubyte3_e32 v213, v166
	v_cvt_f32_ubyte0_e32 v214, v170
	v_cvt_f32_ubyte1_e32 v215, v170
	v_cvt_f32_ubyte2_e32 v218, v170
	v_cvt_f32_ubyte3_e32 v219, v170
	v_rcp_iflag_f32_e32 v214, v214
	v_rcp_iflag_f32_e32 v215, v215
	v_rcp_iflag_f32_e32 v218, v218
	v_rcp_iflag_f32_e32 v219, v219
	v_mul_f32_e32 v210, v214, v210
	v_mul_f32_e32 v211, v215, v211
	v_mul_f32_e32 v212, v218, v212
	v_mul_f32_e32 v213, v219, v213
	v_pk_mul_f32 v[106:107], v[106:107], v[210:211]
	v_pk_mul_f32 v[108:109], v[108:109], v[212:213]
	v_cvt_f32_ubyte0_e32 v210, v167
	v_cvt_f32_ubyte1_e32 v211, v167
	v_cvt_f32_ubyte2_e32 v212, v167
	v_cvt_f32_ubyte3_e32 v213, v167
	v_cvt_f32_ubyte0_e32 v214, v171
	v_cvt_f32_ubyte1_e32 v215, v171
	v_cvt_f32_ubyte2_e32 v218, v171
	v_cvt_f32_ubyte3_e32 v219, v171
	v_rcp_iflag_f32_e32 v214, v214
	v_rcp_iflag_f32_e32 v215, v215
	v_rcp_iflag_f32_e32 v218, v218
	v_rcp_iflag_f32_e32 v219, v219
	v_mul_f32_e32 v210, v214, v210
	v_mul_f32_e32 v211, v215, v211
	v_mul_f32_e32 v212, v218, v212
	v_mul_f32_e32 v213, v219, v213
	v_pk_mul_f32 v[102:103], v[102:103], v[210:211]
	v_pk_mul_f32 v[104:105], v[104:105], v[212:213]
	v_cvt_f32_ubyte0_e32 v210, v168
	v_cvt_f32_ubyte1_e32 v211, v168
	v_cvt_f32_ubyte2_e32 v212, v168
	v_cvt_f32_ubyte3_e32 v213, v168
	v_cvt_f32_ubyte0_e32 v214, v172
	v_cvt_f32_ubyte1_e32 v215, v172
	v_cvt_f32_ubyte2_e32 v218, v172
	v_cvt_f32_ubyte3_e32 v219, v172
	v_rcp_iflag_f32_e32 v214, v214
	v_rcp_iflag_f32_e32 v215, v215
	v_rcp_iflag_f32_e32 v218, v218
	v_rcp_iflag_f32_e32 v219, v219
	v_mul_f32_e32 v210, v214, v210
	v_mul_f32_e32 v211, v215, v211
	v_mul_f32_e32 v212, v218, v212
	v_mul_f32_e32 v213, v219, v213
	v_pk_mul_f32 v[74:75], v[74:75], v[210:211]
	v_pk_mul_f32 v[76:77], v[76:77], v[212:213]
	v_cvt_f32_ubyte0_e32 v210, v169
	v_cvt_f32_ubyte1_e32 v211, v169
	v_cvt_f32_ubyte2_e32 v212, v169
	v_cvt_f32_ubyte3_e32 v213, v169
	v_cvt_f32_ubyte0_e32 v214, v173
	v_cvt_f32_ubyte1_e32 v215, v173
	v_cvt_f32_ubyte2_e32 v218, v173
	v_cvt_f32_ubyte3_e32 v219, v173
	v_rcp_iflag_f32_e32 v214, v214
	v_rcp_iflag_f32_e32 v215, v215
	v_rcp_iflag_f32_e32 v218, v218
	v_rcp_iflag_f32_e32 v219, v219
	v_mul_f32_e32 v210, v214, v210
	v_mul_f32_e32 v211, v215, v211
	v_mul_f32_e32 v212, v218, v212
	v_mul_f32_e32 v213, v219, v213
	v_pk_mul_f32 v[70:71], v[70:71], v[210:211]
	v_pk_mul_f32 v[72:73], v[72:73], v[212:213]
	v_cvt_f32_ubyte0_e32 v210, v158
	v_cvt_f32_ubyte1_e32 v211, v158
	v_cvt_f32_ubyte2_e32 v212, v158
	v_cvt_f32_ubyte3_e32 v213, v158
	v_cvt_f32_ubyte0_e32 v214, v162
	v_cvt_f32_ubyte1_e32 v215, v162
	v_cvt_f32_ubyte2_e32 v218, v162
	v_cvt_f32_ubyte3_e32 v219, v162
	v_rcp_iflag_f32_e32 v214, v214
	v_rcp_iflag_f32_e32 v215, v215
	v_rcp_iflag_f32_e32 v218, v218
	v_rcp_iflag_f32_e32 v219, v219
	v_mul_f32_e32 v210, v214, v210
	v_mul_f32_e32 v211, v215, v211
	v_mul_f32_e32 v212, v218, v212
	v_mul_f32_e32 v213, v219, v213
	v_pk_mul_f32 v[66:67], v[66:67], v[210:211]
	v_pk_mul_f32 v[68:69], v[68:69], v[212:213]
	v_cvt_f32_ubyte0_e32 v210, v159
	v_cvt_f32_ubyte1_e32 v211, v159
	v_cvt_f32_ubyte2_e32 v212, v159
	v_cvt_f32_ubyte3_e32 v213, v159
	v_cvt_f32_ubyte0_e32 v214, v163
	v_cvt_f32_ubyte1_e32 v215, v163
	v_cvt_f32_ubyte2_e32 v218, v163
	v_cvt_f32_ubyte3_e32 v219, v163
	v_rcp_iflag_f32_e32 v214, v214
	v_rcp_iflag_f32_e32 v215, v215
	v_rcp_iflag_f32_e32 v218, v218
	v_rcp_iflag_f32_e32 v219, v219
	v_mul_f32_e32 v210, v214, v210
	v_mul_f32_e32 v211, v215, v211
	v_mul_f32_e32 v212, v218, v212
	v_mul_f32_e32 v213, v219, v213
	v_pk_mul_f32 v[62:63], v[62:63], v[210:211]
	v_pk_mul_f32 v[64:65], v[64:65], v[212:213]
	v_cvt_f32_ubyte0_e32 v210, v160
	v_cvt_f32_ubyte1_e32 v211, v160
	v_cvt_f32_ubyte2_e32 v212, v160
	v_cvt_f32_ubyte3_e32 v213, v160
	v_cvt_f32_ubyte0_e32 v214, v164
	v_cvt_f32_ubyte1_e32 v215, v164
	v_cvt_f32_ubyte2_e32 v218, v164
	v_cvt_f32_ubyte3_e32 v219, v164
	v_rcp_iflag_f32_e32 v214, v214
	v_rcp_iflag_f32_e32 v215, v215
	v_rcp_iflag_f32_e32 v218, v218
	v_rcp_iflag_f32_e32 v219, v219
	v_mul_f32_e32 v210, v214, v210
	v_mul_f32_e32 v211, v215, v211
	v_mul_f32_e32 v212, v218, v212
	v_mul_f32_e32 v213, v219, v213
	v_pk_mul_f32 v[28:29], v[28:29], v[210:211]
	v_pk_mul_f32 v[30:31], v[30:31], v[212:213]
	v_cvt_f32_ubyte0_e32 v210, v161
	v_cvt_f32_ubyte1_e32 v211, v161
	v_cvt_f32_ubyte2_e32 v212, v161
	v_cvt_f32_ubyte3_e32 v213, v161
	v_cvt_f32_ubyte0_e32 v214, v165
	v_cvt_f32_ubyte1_e32 v215, v165
	v_cvt_f32_ubyte2_e32 v218, v165
	v_cvt_f32_ubyte3_e32 v219, v165
	v_rcp_iflag_f32_e32 v214, v214
	v_rcp_iflag_f32_e32 v215, v215
	v_rcp_iflag_f32_e32 v218, v218
	v_rcp_iflag_f32_e32 v219, v219
	v_mul_f32_e32 v210, v214, v210
	v_mul_f32_e32 v211, v215, v211
	v_mul_f32_e32 v212, v218, v212
	v_mul_f32_e32 v213, v219, v213
	v_pk_mul_f32 v[24:25], v[24:25], v[210:211]
	v_pk_mul_f32 v[26:27], v[26:27], v[212:213]
	v_cvt_f32_ubyte0_e32 v210, v150
	v_cvt_f32_ubyte1_e32 v211, v150
	v_cvt_f32_ubyte2_e32 v212, v150
	v_cvt_f32_ubyte3_e32 v213, v150
	v_cvt_f32_ubyte0_e32 v214, v154
	v_cvt_f32_ubyte1_e32 v215, v154
	v_cvt_f32_ubyte2_e32 v218, v154
	v_cvt_f32_ubyte3_e32 v219, v154
	v_rcp_iflag_f32_e32 v214, v214
	v_rcp_iflag_f32_e32 v215, v215
	v_rcp_iflag_f32_e32 v218, v218
	v_rcp_iflag_f32_e32 v219, v219
	v_mul_f32_e32 v210, v214, v210
	v_mul_f32_e32 v211, v215, v211
	v_mul_f32_e32 v212, v218, v212
	v_mul_f32_e32 v213, v219, v213
	v_pk_mul_f32 v[58:59], v[58:59], v[210:211]
	v_pk_mul_f32 v[60:61], v[60:61], v[212:213]
	v_cvt_f32_ubyte0_e32 v210, v151
	v_cvt_f32_ubyte1_e32 v211, v151
	v_cvt_f32_ubyte2_e32 v212, v151
	v_cvt_f32_ubyte3_e32 v213, v151
	v_cvt_f32_ubyte0_e32 v214, v155
	v_cvt_f32_ubyte1_e32 v215, v155
	v_cvt_f32_ubyte2_e32 v218, v155
	v_cvt_f32_ubyte3_e32 v219, v155
	v_rcp_iflag_f32_e32 v214, v214
	v_rcp_iflag_f32_e32 v215, v215
	v_rcp_iflag_f32_e32 v218, v218
	v_rcp_iflag_f32_e32 v219, v219
	v_mul_f32_e32 v210, v214, v210
	v_mul_f32_e32 v211, v215, v211
	v_mul_f32_e32 v212, v218, v212
	v_mul_f32_e32 v213, v219, v213
	v_pk_mul_f32 v[54:55], v[54:55], v[210:211]
	v_pk_mul_f32 v[56:57], v[56:57], v[212:213]
	v_cvt_f32_ubyte0_e32 v210, v152
	v_cvt_f32_ubyte1_e32 v211, v152
	v_cvt_f32_ubyte2_e32 v212, v152
	v_cvt_f32_ubyte3_e32 v213, v152
	v_cvt_f32_ubyte0_e32 v214, v156
	v_cvt_f32_ubyte1_e32 v215, v156
	v_cvt_f32_ubyte2_e32 v218, v156
	v_cvt_f32_ubyte3_e32 v219, v156
	v_rcp_iflag_f32_e32 v214, v214
	v_rcp_iflag_f32_e32 v215, v215
	v_rcp_iflag_f32_e32 v218, v218
	v_rcp_iflag_f32_e32 v219, v219
	v_mul_f32_e32 v210, v214, v210
	v_mul_f32_e32 v211, v215, v211
	v_mul_f32_e32 v212, v218, v212
	v_mul_f32_e32 v213, v219, v213
	v_pk_mul_f32 v[20:21], v[20:21], v[210:211]
	v_pk_mul_f32 v[22:23], v[22:23], v[212:213]
	v_cvt_f32_ubyte0_e32 v210, v153
	v_cvt_f32_ubyte1_e32 v211, v153
	v_cvt_f32_ubyte2_e32 v212, v153
	v_cvt_f32_ubyte3_e32 v213, v153
	v_cvt_f32_ubyte0_e32 v214, v157
	v_cvt_f32_ubyte1_e32 v215, v157
	v_cvt_f32_ubyte2_e32 v218, v157
	v_cvt_f32_ubyte3_e32 v219, v157
	v_rcp_iflag_f32_e32 v214, v214
	v_rcp_iflag_f32_e32 v215, v215
	v_rcp_iflag_f32_e32 v218, v218
	v_rcp_iflag_f32_e32 v219, v219
	v_mul_f32_e32 v210, v214, v210
	v_mul_f32_e32 v211, v215, v211
	v_mul_f32_e32 v212, v218, v212
	v_mul_f32_e32 v213, v219, v213
	v_pk_mul_f32 v[16:17], v[16:17], v[210:211]
	v_pk_mul_f32 v[18:19], v[18:19], v[212:213]
	v_cvt_f32_ubyte0_e32 v210, v142
	v_cvt_f32_ubyte1_e32 v211, v142
	v_cvt_f32_ubyte2_e32 v212, v142
	v_cvt_f32_ubyte3_e32 v213, v142
	v_cvt_f32_ubyte0_e32 v214, v146
	v_cvt_f32_ubyte1_e32 v215, v146
	v_cvt_f32_ubyte2_e32 v218, v146
	v_cvt_f32_ubyte3_e32 v219, v146
	v_rcp_iflag_f32_e32 v214, v214
	v_rcp_iflag_f32_e32 v215, v215
	v_rcp_iflag_f32_e32 v218, v218
	v_rcp_iflag_f32_e32 v219, v219
	v_mul_f32_e32 v210, v214, v210
	v_mul_f32_e32 v211, v215, v211
	v_mul_f32_e32 v212, v218, v212
	v_mul_f32_e32 v213, v219, v213
	v_pk_mul_f32 v[50:51], v[50:51], v[210:211]
	v_pk_mul_f32 v[52:53], v[52:53], v[212:213]
	v_cvt_f32_ubyte0_e32 v210, v143
	v_cvt_f32_ubyte1_e32 v211, v143
	v_cvt_f32_ubyte2_e32 v212, v143
	v_cvt_f32_ubyte3_e32 v213, v143
	v_cvt_f32_ubyte0_e32 v214, v147
	v_cvt_f32_ubyte1_e32 v215, v147
	v_cvt_f32_ubyte2_e32 v218, v147
	v_cvt_f32_ubyte3_e32 v219, v147
	v_rcp_iflag_f32_e32 v214, v214
	v_rcp_iflag_f32_e32 v215, v215
	v_rcp_iflag_f32_e32 v218, v218
	v_rcp_iflag_f32_e32 v219, v219
	v_mul_f32_e32 v210, v214, v210
	v_mul_f32_e32 v211, v215, v211
	v_mul_f32_e32 v212, v218, v212
	v_mul_f32_e32 v213, v219, v213
	v_pk_mul_f32 v[46:47], v[46:47], v[210:211]
	v_pk_mul_f32 v[48:49], v[48:49], v[212:213]
	v_cvt_f32_ubyte0_e32 v210, v144
	v_cvt_f32_ubyte1_e32 v211, v144
	v_cvt_f32_ubyte2_e32 v212, v144
	v_cvt_f32_ubyte3_e32 v213, v144
	v_cvt_f32_ubyte0_e32 v214, v148
	v_cvt_f32_ubyte1_e32 v215, v148
	v_cvt_f32_ubyte2_e32 v218, v148
	v_cvt_f32_ubyte3_e32 v219, v148
	v_rcp_iflag_f32_e32 v214, v214
	v_rcp_iflag_f32_e32 v215, v215
	v_rcp_iflag_f32_e32 v218, v218
	v_rcp_iflag_f32_e32 v219, v219
	v_mul_f32_e32 v210, v214, v210
	v_mul_f32_e32 v211, v215, v211
	v_mul_f32_e32 v212, v218, v212
	v_mul_f32_e32 v213, v219, v213
	v_pk_mul_f32 v[12:13], v[12:13], v[210:211]
	v_pk_mul_f32 v[14:15], v[14:15], v[212:213]
	v_cvt_f32_ubyte0_e32 v210, v145
	v_cvt_f32_ubyte1_e32 v211, v145
	v_cvt_f32_ubyte2_e32 v212, v145
	v_cvt_f32_ubyte3_e32 v213, v145
	v_cvt_f32_ubyte0_e32 v214, v149
	v_cvt_f32_ubyte1_e32 v215, v149
	v_cvt_f32_ubyte2_e32 v218, v149
	v_cvt_f32_ubyte3_e32 v219, v149
	v_rcp_iflag_f32_e32 v214, v214
	v_rcp_iflag_f32_e32 v215, v215
	v_rcp_iflag_f32_e32 v218, v218
	v_rcp_iflag_f32_e32 v219, v219
	v_mul_f32_e32 v210, v214, v210
	v_mul_f32_e32 v211, v215, v211
	v_mul_f32_e32 v212, v218, v212
	v_mul_f32_e32 v213, v219, v213
	v_pk_mul_f32 v[8:9], v[8:9], v[210:211]
	v_pk_mul_f32 v[10:11], v[10:11], v[212:213]
	v_cvt_f32_ubyte0_e32 v210, v134
	v_cvt_f32_ubyte1_e32 v211, v134
	v_cvt_f32_ubyte2_e32 v212, v134
	v_cvt_f32_ubyte3_e32 v213, v134
	v_cvt_f32_ubyte0_e32 v214, v138
	v_cvt_f32_ubyte1_e32 v215, v138
	v_cvt_f32_ubyte2_e32 v218, v138
	v_cvt_f32_ubyte3_e32 v219, v138
	v_rcp_iflag_f32_e32 v214, v214
	v_rcp_iflag_f32_e32 v215, v215
	v_rcp_iflag_f32_e32 v218, v218
	v_rcp_iflag_f32_e32 v219, v219
	v_mul_f32_e32 v210, v214, v210
	v_mul_f32_e32 v211, v215, v211
	v_mul_f32_e32 v212, v218, v212
	v_mul_f32_e32 v213, v219, v213
	v_pk_mul_f32 v[42:43], v[42:43], v[210:211]
	v_pk_mul_f32 v[44:45], v[44:45], v[212:213]
	v_cvt_f32_ubyte0_e32 v210, v135
	v_cvt_f32_ubyte1_e32 v211, v135
	v_cvt_f32_ubyte2_e32 v212, v135
	v_cvt_f32_ubyte3_e32 v213, v135
	v_cvt_f32_ubyte0_e32 v214, v139
	v_cvt_f32_ubyte1_e32 v215, v139
	v_cvt_f32_ubyte2_e32 v218, v139
	v_cvt_f32_ubyte3_e32 v219, v139
	v_rcp_iflag_f32_e32 v214, v214
	v_rcp_iflag_f32_e32 v215, v215
	v_rcp_iflag_f32_e32 v218, v218
	v_rcp_iflag_f32_e32 v219, v219
	v_mul_f32_e32 v210, v214, v210
	v_mul_f32_e32 v211, v215, v211
	v_mul_f32_e32 v212, v218, v212
	v_mul_f32_e32 v213, v219, v213
	v_pk_mul_f32 v[38:39], v[38:39], v[210:211]
	v_pk_mul_f32 v[40:41], v[40:41], v[212:213]
	v_cvt_f32_ubyte0_e32 v210, v136
	v_cvt_f32_ubyte1_e32 v211, v136
	v_cvt_f32_ubyte2_e32 v212, v136
	v_cvt_f32_ubyte3_e32 v213, v136
	v_cvt_f32_ubyte0_e32 v214, v140
	v_cvt_f32_ubyte1_e32 v215, v140
	v_cvt_f32_ubyte2_e32 v218, v140
	v_cvt_f32_ubyte3_e32 v219, v140
	v_rcp_iflag_f32_e32 v214, v214
	v_rcp_iflag_f32_e32 v215, v215
	v_rcp_iflag_f32_e32 v218, v218
	v_rcp_iflag_f32_e32 v219, v219
	v_mul_f32_e32 v210, v214, v210
	v_mul_f32_e32 v211, v215, v211
	v_mul_f32_e32 v212, v218, v212
	v_mul_f32_e32 v213, v219, v213
	v_pk_mul_f32 v[4:5], v[4:5], v[210:211]
	v_pk_mul_f32 v[6:7], v[6:7], v[212:213]
	v_cvt_f32_ubyte0_e32 v210, v137
	v_cvt_f32_ubyte1_e32 v211, v137
	v_cvt_f32_ubyte2_e32 v212, v137
	v_cvt_f32_ubyte3_e32 v213, v137
	v_cvt_f32_ubyte0_e32 v214, v141
	v_cvt_f32_ubyte1_e32 v215, v141
	v_cvt_f32_ubyte2_e32 v218, v141
	v_cvt_f32_ubyte3_e32 v219, v141
	v_rcp_iflag_f32_e32 v214, v214
	v_rcp_iflag_f32_e32 v215, v215
	v_rcp_iflag_f32_e32 v218, v218
	v_rcp_iflag_f32_e32 v219, v219
	v_mul_f32_e32 v210, v214, v210
	v_mul_f32_e32 v211, v215, v211
	v_mul_f32_e32 v212, v218, v212
	v_mul_f32_e32 v213, v219, v213
	v_pk_mul_f32 v[0:1], v[0:1], v[210:211]
	v_pk_mul_f32 v[2:3], v[2:3], v[212:213]
	s_branch .LBB0_1465
.Lwo_eq3:
	s_waitcnt vmcnt(0)
	s_lshl_b32 s0, s73, 9
	s_lshl_b32 s12, s72, 19
	s_add_i32 s12, s12, s0
	v_add_u32_e32 v245, s12, v243
	s_mov_b32 s0, 0x0
	v_cvt_f32_ubyte0_e32 v210, v190
	v_cvt_f32_ubyte1_e32 v211, v190
	v_cvt_f32_ubyte2_e32 v212, v190
	v_cvt_f32_ubyte3_e32 v213, v190
	v_mul_f32_e32 v210, 0x3b800000, v210
	v_mul_f32_e32 v211, 0x3b800000, v211
	v_mul_f32_e32 v212, 0x3b800000, v212
	v_mul_f32_e32 v213, 0x3b800000, v213
	v_pk_mul_f32 v[130:131], v[130:131], v[210:211]
	v_pk_mul_f32 v[132:133], v[132:133], v[212:213]
	v_cvt_f32_ubyte0_e32 v210, v191
	v_cvt_f32_ubyte1_e32 v211, v191
	v_cvt_f32_ubyte2_e32 v212, v191
	v_cvt_f32_ubyte3_e32 v213, v191
	v_mul_f32_e32 v210, 0x3b800000, v210
	v_mul_f32_e32 v211, 0x3b800000, v211
	v_mul_f32_e32 v212, 0x3b800000, v212
	v_mul_f32_e32 v213, 0x3b800000, v213
	v_pk_mul_f32 v[126:127], v[126:127], v[210:211]
	v_pk_mul_f32 v[128:129], v[128:129], v[212:213]
	v_cvt_pk_bf16_f32 v218, v130, v131
	v_cvt_pk_bf16_f32 v219, v132, v133
	v_cvt_pk_bf16_f32 v220, v126, v127
	v_cvt_pk_bf16_f32 v221, v128, v129
	buffer_store_dwordx4 v[218:221], v245, s[48:51], s0 offen sc1
	v_cvt_f32_ubyte0_e32 v210, v192
	v_cvt_f32_ubyte1_e32 v211, v192
	v_cvt_f32_ubyte2_e32 v212, v192
	v_cvt_f32_ubyte3_e32 v213, v192
	v_mul_f32_e32 v210, 0x3b800000, v210
	v_mul_f32_e32 v211, 0x3b800000, v211
	v_mul_f32_e32 v212, 0x3b800000, v212
	v_mul_f32_e32 v213, 0x3b800000, v213
	v_pk_mul_f32 v[98:99], v[98:99], v[210:211]
	v_pk_mul_f32 v[100:101], v[100:101], v[212:213]
	v_cvt_f32_ubyte0_e32 v210, v193
	v_cvt_f32_ubyte1_e32 v211, v193
	v_cvt_f32_ubyte2_e32 v212, v193
	v_cvt_f32_ubyte3_e32 v213, v193
	v_mul_f32_e32 v210, 0x3b800000, v210
	v_mul_f32_e32 v211, 0x3b800000, v211
	v_mul_f32_e32 v212, 0x3b800000, v212
	v_mul_f32_e32 v213, 0x3b800000, v213
	v_pk_mul_f32 v[94:95], v[94:95], v[210:211]
	v_pk_mul_f32 v[96:97], v[96:97], v[212:213]
	v_cvt_pk_bf16_f32 v218, v98, v99
	v_cvt_pk_bf16_f32 v219, v100, v101
	v_cvt_pk_bf16_f32 v220, v94, v95
	v_cvt_pk_bf16_f32 v221, v96, v97
	buffer_store_dwordx4 v[218:221], v245, s[48:51], s0 offen offset:256 sc1
	s_mov_b32 s0, 0x8000
	v_cvt_f32_ubyte0_e32 v210, v182
	v_cvt_f32_ubyte1_e32 v211, v182
	v_cvt_f32_ubyte2_e32 v212, v182
	v_cvt_f32_ubyte3_e32 v213, v182
	v_mul_f32_e32 v210, 0x3b800000, v210
	v_mul_f32_e32 v211, 0x3b800000, v211
	v_mul_f32_e32 v212, 0x3b800000, v212
	v_mul_f32_e32 v213, 0x3b800000, v213
	v_pk_mul_f32 v[122:123], v[122:123], v[210:211]
	v_pk_mul_f32 v[124:125], v[124:125], v[212:213]
	v_cvt_f32_ubyte0_e32 v210, v183
	v_cvt_f32_ubyte1_e32 v211, v183
	v_cvt_f32_ubyte2_e32 v212, v183
	v_cvt_f32_ubyte3_e32 v213, v183
	v_mul_f32_e32 v210, 0x3b800000, v210
	v_mul_f32_e32 v211, 0x3b800000, v211
	v_mul_f32_e32 v212, 0x3b800000, v212
	v_mul_f32_e32 v213, 0x3b800000, v213
	v_pk_mul_f32 v[118:119], v[118:119], v[210:211]
	v_pk_mul_f32 v[120:121], v[120:121], v[212:213]
	v_cvt_pk_bf16_f32 v218, v122, v123
	v_cvt_pk_bf16_f32 v219, v124, v125
	v_cvt_pk_bf16_f32 v220, v118, v119
	v_cvt_pk_bf16_f32 v221, v120, v121
	buffer_store_dwordx4 v[218:221], v245, s[48:51], s0 offen sc1
	v_cvt_f32_ubyte0_e32 v210, v184
	v_cvt_f32_ubyte1_e32 v211, v184
	v_cvt_f32_ubyte2_e32 v212, v184
	v_cvt_f32_ubyte3_e32 v213, v184
	v_mul_f32_e32 v210, 0x3b800000, v210
	v_mul_f32_e32 v211, 0x3b800000, v211
	v_mul_f32_e32 v212, 0x3b800000, v212
	v_mul_f32_e32 v213, 0x3b800000, v213
	v_pk_mul_f32 v[90:91], v[90:91], v[210:211]
	v_pk_mul_f32 v[92:93], v[92:93], v[212:213]
	v_cvt_f32_ubyte0_e32 v210, v185
	v_cvt_f32_ubyte1_e32 v211, v185
	v_cvt_f32_ubyte2_e32 v212, v185
	v_cvt_f32_ubyte3_e32 v213, v185
	v_mul_f32_e32 v210, 0x3b800000, v210
	v_mul_f32_e32 v211, 0x3b800000, v211
	v_mul_f32_e32 v212, 0x3b800000, v212
	v_mul_f32_e32 v213, 0x3b800000, v213
	v_pk_mul_f32 v[86:87], v[86:87], v[210:211]
	v_pk_mul_f32 v[88:89], v[88:89], v[212:213]
	v_cvt_pk_bf16_f32 v218, v90, v91
	v_cvt_pk_bf16_f32 v219, v92, v93
	v_cvt_pk_bf16_f32 v220, v86, v87
	v_cvt_pk_bf16_f32 v221, v88, v89
	buffer_store_dwordx4 v[218:221], v245, s[48:51], s0 offen offset:256 sc1
	s_mov_b32 s0, 0x10000
	v_cvt_f32_ubyte0_e32 v210, v174
	v_cvt_f32_ubyte1_e32 v211, v174
	v_cvt_f32_ubyte2_e32 v212, v174
	v_cvt_f32_ubyte3_e32 v213, v174
	v_mul_f32_e32 v210, 0x3b800000, v210
	v_mul_f32_e32 v211, 0x3b800000, v211
	v_mul_f32_e32 v212, 0x3b800000, v212
	v_mul_f32_e32 v213, 0x3b800000, v213
	v_pk_mul_f32 v[114:115], v[114:115], v[210:211]
	v_pk_mul_f32 v[116:117], v[116:117], v[212:213]
	v_cvt_f32_ubyte0_e32 v210, v175
	v_cvt_f32_ubyte1_e32 v211, v175
	v_cvt_f32_ubyte2_e32 v212, v175
	v_cvt_f32_ubyte3_e32 v213, v175
	v_mul_f32_e32 v210, 0x3b800000, v210
	v_mul_f32_e32 v211, 0x3b800000, v211
	v_mul_f32_e32 v212, 0x3b800000, v212
	v_mul_f32_e32 v213, 0x3b800000, v213
	v_pk_mul_f32 v[110:111], v[110:111], v[210:211]
	v_pk_mul_f32 v[112:113], v[112:113], v[212:213]
	v_cvt_pk_bf16_f32 v218, v114, v115
	v_cvt_pk_bf16_f32 v219, v116, v117
	v_cvt_pk_bf16_f32 v220, v110, v111
	v_cvt_pk_bf16_f32 v221, v112, v113
	buffer_store_dwordx4 v[218:221], v245, s[48:51], s0 offen sc1
	v_cvt_f32_ubyte0_e32 v210, v176
	v_cvt_f32_ubyte1_e32 v211, v176
	v_cvt_f32_ubyte2_e32 v212, v176
	v_cvt_f32_ubyte3_e32 v213, v176
	v_mul_f32_e32 v210, 0x3b800000, v210
	v_mul_f32_e32 v211, 0x3b800000, v211
	v_mul_f32_e32 v212, 0x3b800000, v212
	v_mul_f32_e32 v213, 0x3b800000, v213
	v_pk_mul_f32 v[82:83], v[82:83], v[210:211]
	v_pk_mul_f32 v[84:85], v[84:85], v[212:213]
	v_cvt_f32_ubyte0_e32 v210, v177
	v_cvt_f32_ubyte1_e32 v211, v177
	v_cvt_f32_ubyte2_e32 v212, v177
	v_cvt_f32_ubyte3_e32 v213, v177
	v_mul_f32_e32 v210, 0x3b800000, v210
	v_mul_f32_e32 v211, 0x3b800000, v211
	v_mul_f32_e32 v212, 0x3b800000, v212
	v_mul_f32_e32 v213, 0x3b800000, v213
	v_pk_mul_f32 v[78:79], v[78:79], v[210:211]
	v_pk_mul_f32 v[80:81], v[80:81], v[212:213]
	v_cvt_pk_bf16_f32 v218, v82, v83
	v_cvt_pk_bf16_f32 v219, v84, v85
	v_cvt_pk_bf16_f32 v220, v78, v79
	v_cvt_pk_bf16_f32 v221, v80, v81
	buffer_store_dwordx4 v[218:221], v245, s[48:51], s0 offen offset:256 sc1
	s_mov_b32 s0, 0x18000
	v_cvt_f32_ubyte0_e32 v210, v166
	v_cvt_f32_ubyte1_e32 v211, v166
	v_cvt_f32_ubyte2_e32 v212, v166
	v_cvt_f32_ubyte3_e32 v213, v166
	v_mul_f32_e32 v210, 0x3b800000, v210
	v_mul_f32_e32 v211, 0x3b800000, v211
	v_mul_f32_e32 v212, 0x3b800000, v212
	v_mul_f32_e32 v213, 0x3b800000, v213
	v_pk_mul_f32 v[106:107], v[106:107], v[210:211]
	v_pk_mul_f32 v[108:109], v[108:109], v[212:213]
	v_cvt_f32_ubyte0_e32 v210, v167
	v_cvt_f32_ubyte1_e32 v211, v167
	v_cvt_f32_ubyte2_e32 v212, v167
	v_cvt_f32_ubyte3_e32 v213, v167
	v_mul_f32_e32 v210, 0x3b800000, v210
	v_mul_f32_e32 v211, 0x3b800000, v211
	v_mul_f32_e32 v212, 0x3b800000, v212
	v_mul_f32_e32 v213, 0x3b800000, v213
	v_pk_mul_f32 v[102:103], v[102:103], v[210:211]
	v_pk_mul_f32 v[104:105], v[104:105], v[212:213]
	v_cvt_pk_bf16_f32 v218, v106, v107
	v_cvt_pk_bf16_f32 v219, v108, v109
	v_cvt_pk_bf16_f32 v220, v102, v103
	v_cvt_pk_bf16_f32 v221, v104, v105
	buffer_store_dwordx4 v[218:221], v245, s[48:51], s0 offen sc1
	v_cvt_f32_ubyte0_e32 v210, v168
	v_cvt_f32_ubyte1_e32 v211, v168
	v_cvt_f32_ubyte2_e32 v212, v168
	v_cvt_f32_ubyte3_e32 v213, v168
	v_mul_f32_e32 v210, 0x3b800000, v210
	v_mul_f32_e32 v211, 0x3b800000, v211
	v_mul_f32_e32 v212, 0x3b800000, v212
	v_mul_f32_e32 v213, 0x3b800000, v213
	v_pk_mul_f32 v[74:75], v[74:75], v[210:211]
	v_pk_mul_f32 v[76:77], v[76:77], v[212:213]
	v_cvt_f32_ubyte0_e32 v210, v169
	v_cvt_f32_ubyte1_e32 v211, v169
	v_cvt_f32_ubyte2_e32 v212, v169
	v_cvt_f32_ubyte3_e32 v213, v169
	v_mul_f32_e32 v210, 0x3b800000, v210
	v_mul_f32_e32 v211, 0x3b800000, v211
	v_mul_f32_e32 v212, 0x3b800000, v212
	v_mul_f32_e32 v213, 0x3b800000, v213
	v_pk_mul_f32 v[70:71], v[70:71], v[210:211]
	v_pk_mul_f32 v[72:73], v[72:73], v[212:213]
	v_cvt_pk_bf16_f32 v218, v74, v75
	v_cvt_pk_bf16_f32 v219, v76, v77
	v_cvt_pk_bf16_f32 v220, v70, v71
	v_cvt_pk_bf16_f32 v221, v72, v73
	buffer_store_dwordx4 v[218:221], v245, s[48:51], s0 offen offset:256 sc1
	s_mov_b32 s0, 0x40000
	v_cvt_f32_ubyte0_e32 v210, v158
	v_cvt_f32_ubyte1_e32 v211, v158
	v_cvt_f32_ubyte2_e32 v212, v158
	v_cvt_f32_ubyte3_e32 v213, v158
	v_mul_f32_e32 v210, 0x3b800000, v210
	v_mul_f32_e32 v211, 0x3b800000, v211
	v_mul_f32_e32 v212, 0x3b800000, v212
	v_mul_f32_e32 v213, 0x3b800000, v213
	v_pk_mul_f32 v[66:67], v[66:67], v[210:211]
	v_pk_mul_f32 v[68:69], v[68:69], v[212:213]
	v_cvt_f32_ubyte0_e32 v210, v159
	v_cvt_f32_ubyte1_e32 v211, v159
	v_cvt_f32_ubyte2_e32 v212, v159
	v_cvt_f32_ubyte3_e32 v213, v159
	v_mul_f32_e32 v210, 0x3b800000, v210
	v_mul_f32_e32 v211, 0x3b800000, v211
	v_mul_f32_e32 v212, 0x3b800000, v212
	v_mul_f32_e32 v213, 0x3b800000, v213
	v_pk_mul_f32 v[62:63], v[62:63], v[210:211]
	v_pk_mul_f32 v[64:65], v[64:65], v[212:213]
	v_cvt_pk_bf16_f32 v218, v66, v67
	v_cvt_pk_bf16_f32 v219, v68, v69
	v_cvt_pk_bf16_f32 v220, v62, v63
	v_cvt_pk_bf16_f32 v221, v64, v65
	buffer_store_dwordx4 v[218:221], v245, s[48:51], s0 offen sc1
	v_cvt_f32_ubyte0_e32 v210, v160
	v_cvt_f32_ubyte1_e32 v211, v160
	v_cvt_f32_ubyte2_e32 v212, v160
	v_cvt_f32_ubyte3_e32 v213, v160
	v_mul_f32_e32 v210, 0x3b800000, v210
	v_mul_f32_e32 v211, 0x3b800000, v211
	v_mul_f32_e32 v212, 0x3b800000, v212
	v_mul_f32_e32 v213, 0x3b800000, v213
	v_pk_mul_f32 v[28:29], v[28:29], v[210:211]
	v_pk_mul_f32 v[30:31], v[30:31], v[212:213]
	v_cvt_f32_ubyte0_e32 v210, v161
	v_cvt_f32_ubyte1_e32 v211, v161
	v_cvt_f32_ubyte2_e32 v212, v161
	v_cvt_f32_ubyte3_e32 v213, v161
	v_mul_f32_e32 v210, 0x3b800000, v210
	v_mul_f32_e32 v211, 0x3b800000, v211
	v_mul_f32_e32 v212, 0x3b800000, v212
	v_mul_f32_e32 v213, 0x3b800000, v213
	v_pk_mul_f32 v[24:25], v[24:25], v[210:211]
	v_pk_mul_f32 v[26:27], v[26:27], v[212:213]
	v_cvt_pk_bf16_f32 v218, v28, v29
	v_cvt_pk_bf16_f32 v219, v30, v31
	v_cvt_pk_bf16_f32 v220, v24, v25
	v_cvt_pk_bf16_f32 v221, v26, v27
	buffer_store_dwordx4 v[218:221], v245, s[48:51], s0 offen offset:256 sc1
	s_mov_b32 s0, 0x48000
	v_cvt_f32_ubyte0_e32 v210, v150
	v_cvt_f32_ubyte1_e32 v211, v150
	v_cvt_f32_ubyte2_e32 v212, v150
	v_cvt_f32_ubyte3_e32 v213, v150
	v_mul_f32_e32 v210, 0x3b800000, v210
	v_mul_f32_e32 v211, 0x3b800000, v211
	v_mul_f32_e32 v212, 0x3b800000, v212
	v_mul_f32_e32 v213, 0x3b800000, v213
	v_pk_mul_f32 v[58:59], v[58:59], v[210:211]
	v_pk_mul_f32 v[60:61], v[60:61], v[212:213]
	v_cvt_f32_ubyte0_e32 v210, v151
	v_cvt_f32_ubyte1_e32 v211, v151
	v_cvt_f32_ubyte2_e32 v212, v151
	v_cvt_f32_ubyte3_e32 v213, v151
	v_mul_f32_e32 v210, 0x3b800000, v210
	v_mul_f32_e32 v211, 0x3b800000, v211
	v_mul_f32_e32 v212, 0x3b800000, v212
	v_mul_f32_e32 v213, 0x3b800000, v213
	v_pk_mul_f32 v[54:55], v[54:55], v[210:211]
	v_pk_mul_f32 v[56:57], v[56:57], v[212:213]
	v_cvt_pk_bf16_f32 v218, v58, v59
	v_cvt_pk_bf16_f32 v219, v60, v61
	v_cvt_pk_bf16_f32 v220, v54, v55
	v_cvt_pk_bf16_f32 v221, v56, v57
	buffer_store_dwordx4 v[218:221], v245, s[48:51], s0 offen sc1
	v_cvt_f32_ubyte0_e32 v210, v152
	v_cvt_f32_ubyte1_e32 v211, v152
	v_cvt_f32_ubyte2_e32 v212, v152
	v_cvt_f32_ubyte3_e32 v213, v152
	v_mul_f32_e32 v210, 0x3b800000, v210
	v_mul_f32_e32 v211, 0x3b800000, v211
	v_mul_f32_e32 v212, 0x3b800000, v212
	v_mul_f32_e32 v213, 0x3b800000, v213
	v_pk_mul_f32 v[20:21], v[20:21], v[210:211]
	v_pk_mul_f32 v[22:23], v[22:23], v[212:213]
	v_cvt_f32_ubyte0_e32 v210, v153
	v_cvt_f32_ubyte1_e32 v211, v153
	v_cvt_f32_ubyte2_e32 v212, v153
	v_cvt_f32_ubyte3_e32 v213, v153
	v_mul_f32_e32 v210, 0x3b800000, v210
	v_mul_f32_e32 v211, 0x3b800000, v211
	v_mul_f32_e32 v212, 0x3b800000, v212
	v_mul_f32_e32 v213, 0x3b800000, v213
	v_pk_mul_f32 v[16:17], v[16:17], v[210:211]
	v_pk_mul_f32 v[18:19], v[18:19], v[212:213]
	v_cvt_pk_bf16_f32 v218, v20, v21
	v_cvt_pk_bf16_f32 v219, v22, v23
	v_cvt_pk_bf16_f32 v220, v16, v17
	v_cvt_pk_bf16_f32 v221, v18, v19
	buffer_store_dwordx4 v[218:221], v245, s[48:51], s0 offen offset:256 sc1
	s_mov_b32 s0, 0x50000
	v_cvt_f32_ubyte0_e32 v210, v142
	v_cvt_f32_ubyte1_e32 v211, v142
	v_cvt_f32_ubyte2_e32 v212, v142
	v_cvt_f32_ubyte3_e32 v213, v142
	v_mul_f32_e32 v210, 0x3b800000, v210
	v_mul_f32_e32 v211, 0x3b800000, v211
	v_mul_f32_e32 v212, 0x3b800000, v212
	v_mul_f32_e32 v213, 0x3b800000, v213
	v_pk_mul_f32 v[50:51], v[50:51], v[210:211]
	v_pk_mul_f32 v[52:53], v[52:53], v[212:213]
	v_cvt_f32_ubyte0_e32 v210, v143
	v_cvt_f32_ubyte1_e32 v211, v143
	v_cvt_f32_ubyte2_e32 v212, v143
	v_cvt_f32_ubyte3_e32 v213, v143
	v_mul_f32_e32 v210, 0x3b800000, v210
	v_mul_f32_e32 v211, 0x3b800000, v211
	v_mul_f32_e32 v212, 0x3b800000, v212
	v_mul_f32_e32 v213, 0x3b800000, v213
	v_pk_mul_f32 v[46:47], v[46:47], v[210:211]
	v_pk_mul_f32 v[48:49], v[48:49], v[212:213]
	v_cvt_pk_bf16_f32 v218, v50, v51
	v_cvt_pk_bf16_f32 v219, v52, v53
	v_cvt_pk_bf16_f32 v220, v46, v47
	v_cvt_pk_bf16_f32 v221, v48, v49
	buffer_store_dwordx4 v[218:221], v245, s[48:51], s0 offen sc1
	v_cvt_f32_ubyte0_e32 v210, v144
	v_cvt_f32_ubyte1_e32 v211, v144
	v_cvt_f32_ubyte2_e32 v212, v144
	v_cvt_f32_ubyte3_e32 v213, v144
	v_mul_f32_e32 v210, 0x3b800000, v210
	v_mul_f32_e32 v211, 0x3b800000, v211
	v_mul_f32_e32 v212, 0x3b800000, v212
	v_mul_f32_e32 v213, 0x3b800000, v213
	v_pk_mul_f32 v[12:13], v[12:13], v[210:211]
	v_pk_mul_f32 v[14:15], v[14:15], v[212:213]
	v_cvt_f32_ubyte0_e32 v210, v145
	v_cvt_f32_ubyte1_e32 v211, v145
	v_cvt_f32_ubyte2_e32 v212, v145
	v_cvt_f32_ubyte3_e32 v213, v145
	v_mul_f32_e32 v210, 0x3b800000, v210
	v_mul_f32_e32 v211, 0x3b800000, v211
	v_mul_f32_e32 v212, 0x3b800000, v212
	v_mul_f32_e32 v213, 0x3b800000, v213
	v_pk_mul_f32 v[8:9], v[8:9], v[210:211]
	v_pk_mul_f32 v[10:11], v[10:11], v[212:213]
	v_cvt_pk_bf16_f32 v218, v12, v13
	v_cvt_pk_bf16_f32 v219, v14, v15
	v_cvt_pk_bf16_f32 v220, v8, v9
	v_cvt_pk_bf16_f32 v221, v10, v11
	buffer_store_dwordx4 v[218:221], v245, s[48:51], s0 offen offset:256 sc1
	s_mov_b32 s0, 0x58000
	v_cvt_f32_ubyte0_e32 v210, v134
	v_cvt_f32_ubyte1_e32 v211, v134
	v_cvt_f32_ubyte2_e32 v212, v134
	v_cvt_f32_ubyte3_e32 v213, v134
	v_mul_f32_e32 v210, 0x3b800000, v210
	v_mul_f32_e32 v211, 0x3b800000, v211
	v_mul_f32_e32 v212, 0x3b800000, v212
	v_mul_f32_e32 v213, 0x3b800000, v213
	v_pk_mul_f32 v[42:43], v[42:43], v[210:211]
	v_pk_mul_f32 v[44:45], v[44:45], v[212:213]
	v_cvt_f32_ubyte0_e32 v210, v135
	v_cvt_f32_ubyte1_e32 v211, v135
	v_cvt_f32_ubyte2_e32 v212, v135
	v_cvt_f32_ubyte3_e32 v213, v135
	v_mul_f32_e32 v210, 0x3b800000, v210
	v_mul_f32_e32 v211, 0x3b800000, v211
	v_mul_f32_e32 v212, 0x3b800000, v212
	v_mul_f32_e32 v213, 0x3b800000, v213
	v_pk_mul_f32 v[38:39], v[38:39], v[210:211]
	v_pk_mul_f32 v[40:41], v[40:41], v[212:213]
	v_cvt_pk_bf16_f32 v218, v42, v43
	v_cvt_pk_bf16_f32 v219, v44, v45
	v_cvt_pk_bf16_f32 v220, v38, v39
	v_cvt_pk_bf16_f32 v221, v40, v41
	buffer_store_dwordx4 v[218:221], v245, s[48:51], s0 offen sc1
	v_cvt_f32_ubyte0_e32 v210, v136
	v_cvt_f32_ubyte1_e32 v211, v136
	v_cvt_f32_ubyte2_e32 v212, v136
	v_cvt_f32_ubyte3_e32 v213, v136
	v_mul_f32_e32 v210, 0x3b800000, v210
	v_mul_f32_e32 v211, 0x3b800000, v211
	v_mul_f32_e32 v212, 0x3b800000, v212
	v_mul_f32_e32 v213, 0x3b800000, v213
	v_pk_mul_f32 v[4:5], v[4:5], v[210:211]
	v_pk_mul_f32 v[6:7], v[6:7], v[212:213]
	v_cvt_f32_ubyte0_e32 v210, v137
	v_cvt_f32_ubyte1_e32 v211, v137
	v_cvt_f32_ubyte2_e32 v212, v137
	v_cvt_f32_ubyte3_e32 v213, v137
	v_mul_f32_e32 v210, 0x3b800000, v210
	v_mul_f32_e32 v211, 0x3b800000, v211
	v_mul_f32_e32 v212, 0x3b800000, v212
	v_mul_f32_e32 v213, 0x3b800000, v213
	v_pk_mul_f32 v[0:1], v[0:1], v[210:211]
	v_pk_mul_f32 v[2:3], v[2:3], v[212:213]
	v_cvt_pk_bf16_f32 v218, v4, v5
	v_cvt_pk_bf16_f32 v219, v6, v7
	v_cvt_pk_bf16_f32 v220, v0, v1
	v_cvt_pk_bf16_f32 v221, v2, v3
	buffer_store_dwordx4 v[218:221], v245, s[48:51], s0 offen offset:256 sc1
	s_waitcnt vmcnt(0)
	v_cmp_eq_u32_e32 vcc, 0, v242
	s_and_saveexec_b64 s[12:13], vcc
	s_cbranch_execz .LBB0_1464
	s_mov_b64 s[34:35], exec
	v_mbcnt_lo_u32_b32 v134, s34, 0
	v_mbcnt_hi_u32_b32 v134, s35, v134
	v_cmp_eq_u32_e32 vcc, 0, v134
	s_and_b64 s[72:73], exec, vcc
	s_mov_b64 exec, s[72:73]
	s_cbranch_execz .LBB0_1464
	s_ashr_i32 s39, s38, 31
	s_lshl_b64 s[38:39], s[38:39], 2
	s_add_u32 s38, s55, s38
	s_addc_u32 s39, s56, s39
	s_bcnt1_i32_b64 s0, s[34:35]
	v_mov_b32_e32 v134, s0
	global_atomic_add v33, v134, s[38:39]
